# A,B,C attention loops: V staged in P-native order (no permlane swaps), rare-path running-max update, SGPR-base LDS-DMA addressing, 2-barrier half-tile stagger, bias consts cached (A)
# speedup vs baseline: 1.0202x; 1.0092x over previous
; template <int DQK, int MODE>
; DI void attn_body(const AttnArgs& a, char* lds) {
;     ...
;     auto qkt = [&](f32x16& p0, f32x16& p1, const int kofs) {
;         p0 = f32x16{}; p1 = f32x16{};
;         int kc[NB];
; #pragma unroll
;         for (int i = 0; i < NB; ++i) kc[i] = kb[i] + kofs;
;         bf16x8 fk[2][2]; bf16x8 fq[2];
;         auto rd = [&](auto ic) { constexpr int d0 = decltype(ic)::value; constexpr int sl = d0 & 1;
;             dsr128<(d0 / NB) * (NB * 32)>(fk[sl][0], kc[d0 % NB]); dsr128<(d0 / NB) * (NB * 32) + 32 * KROWB>(fk[sl][1], kc[d0 % NB]);
;             if constexpr (MODE == 2 && d0 >= NQR) dsr128<(d0 - NQR) * 1024>(fq[sl], qra); };
;         rd(std::integral_constant<int, 0>{});
;         cfor<0, ND0>([&](auto ic) { constexpr int d0 = decltype(ic)::value; constexpr int sl = d0 & 1;
;             if constexpr (d0 + 1 < ND0) { rd(std::integral_constant<int, d0 + 1>{}); wait_lgkm<(MODE == 2 && d0 + 1 >= NQR) ? 3 : 2>(); }
;             else wait_lgkm<0>();
;             SBAR();
;             bf16x8 qf; if constexpr (MODE == 2 && d0 >= NQR) qf = fq[sl]; else qf = qr[d0 < NQR ? d0 : 0];
;             p0 = __builtin_amdgcn_mfma_f32_32x32x16_bf16(fk[sl][0], qf, p0, 0, 0, 0);
;             p1 = __builtin_amdgcn_mfma_f32_32x32x16_bf16(fk[sl][1], qf, p1, 0, 0, 0); });
;     };
;     const int qw0 = a.qpos0 + wid * 32;
;     auto partialSM = [&](f32x16& p0, f32x16& p1, float& mn, float& alpha, int k0) {
;         if constexpr (MODE == 1) {
;             const int relmax = k0 + 63 - qw0, relmin = k0 - qw0 - 31;
;             if (relmax <= -128 || relmin >= 128) {
;                 const float bc = a.tab[relmax <= -128 ? 0 : 256];
;                 float pmax = p0[0];
; #pragma unroll
;                 for (int r = 1; r < 16; ++r) pmax = fmaxf(pmax, p0[r]);
; #pragma unroll
;                 for (int r = 0; r < 16; ++r) pmax = fmaxf(pmax, p1[r]);
;                 { auto rr = __builtin_amdgcn_permlane32_swap(__float_as_uint(pmax), __float_as_uint(pmax), false, false);
;                   pmax = fmaxf(__uint_as_float(rr[0]), __uint_as_float(rr[1])); }
;                 pmax = fmaf(pmax, C, bc);
;                 if (__builtin_expect(__all(pmax - m_reg <= THR_L2), 1)) { mn = m_reg; alpha = 1.f; }
;                 else { mn = fmaxf(m_reg, pmax); alpha = __builtin_amdgcn_exp2f(m_reg - mn); m_reg = mn; }
;                 const float off = bc - mn;
.Lprio_skip_1:
	s_or_b64 exec, exec, s[66:67]
	v_subrev_u32_e32 v235, s12, v150
	v_subrev_u32_e32 v236, s12, v152
	v_subrev_u32_e32 v237, s12, v154
	v_add_u32_e32 v237, 0x800, v237
	s_add_u32 s89, s12, 0x170000
	s_addc_u32 s90, s14, 0
	v_mov_b32_e32 v238, s19
	s_mov_b32 s94, 2
	ds_read_b32 v239, v238 offset:1024
	ds_read_b32 v238, v238
	s_waitcnt lgkmcnt(0)
	s_cmp_lt_u32 s16, 0x1000
	s_cbranch_scc0 .Lstg_a_pro
	s_barrier
.Lstg_a_pro:
	s_xor_b64 s[66:67], s[0:1], -1
	v_and_b32_e32 v5, 0x3fffffc0, v161
	s_add_i32 s0, 0, 0x14000
	v_lshl_add_u32 v168, v5, 2, s0
	s_add_i32 s0, 0, 0x8000
	s_cmp_lg_u32 s0, -1
	v_lshlrev_b32_e32 v5, 1, v162
	v_and_b32_e32 v4, 0x100, v4
	s_cselect_b32 s0, s0, 0
	v_and_b32_e32 v3, 0xc0, v3
	s_cmp_lg_u32 0, -1
	v_and_b32_e32 v5, 32, v5
	v_lshlrev_b32_e32 v167, 2, v166
	v_or3_b32 v2, v3, v4, v2
	s_cselect_b32 s36, 0, 0
	v_lshlrev_b32_e32 v6, 3, v165
	v_add3_u32 v174, v5, s36, v2
	v_add_u32_e32 v2, s33, v167
	v_bitop3_b32 v6, v0, v6, s34 bitop3:0x78
	v_lshl_add_u32 v7, v165, 7, s0
	v_sub_u32_e32 v2, v2, v165
	v_mov_b32_e32 v16, v1
	v_mov_b32_e32 v17, v1
	v_add_u32_e32 v170, v6, v7
	v_xad_u32 v171, v6, 32, v7
	v_xad_u32 v172, v6, 64, v7
	v_xad_u32 v173, v6, s13, v7
	v_sub_u32_e32 v175, v2, v163
	v_mov_b32_e32 v2, v1
	v_mov_b32_e32 v3, v1
	v_mov_b32_e32 v4, v1
	v_mov_b32_e32 v5, v1
	v_mov_b32_e32 v6, v1
	v_mov_b32_e32 v7, v1
	v_mov_b32_e32 v8, v1
	v_mov_b32_e32 v9, v1
	v_mov_b32_e32 v10, v1
	v_mov_b32_e32 v11, v1
	v_mov_b32_e32 v12, v1
	v_mov_b32_e32 v13, v1
	v_mov_b32_e32 v14, v1
	v_mov_b32_e32 v15, v1
	v_mov_b64_e32 v[64:65], v[16:17]
	v_mov_b64_e32 v[48:49], v[16:17]
	v_mov_b64_e32 v[32:33], v[16:17]
	s_mov_b32 s17, 0
	s_mov_b32 s35, 64
	v_cmp_gt_u32_e64 s[0:1], 32, v162
	v_lshl_add_u32 v169, v165, 2, v168
	v_sub_u32_e32 v176, s33, v163
	s_nop 0
	v_readfirstlane_b32 s93, v176
	v_mov_b32_e32 v177, 0xf149f2ca
	v_mov_b32_e32 v178, 0
	v_mov_b64_e32 v[62:63], v[14:15]
	v_mov_b64_e32 v[60:61], v[12:13]
	v_mov_b64_e32 v[58:59], v[10:11]
	v_mov_b64_e32 v[56:57], v[8:9]
	v_mov_b64_e32 v[54:55], v[6:7]
	v_mov_b64_e32 v[52:53], v[4:5]
	v_mov_b64_e32 v[50:51], v[2:3]
	v_mov_b64_e32 v[46:47], v[14:15]
	v_mov_b64_e32 v[44:45], v[12:13]
	v_mov_b64_e32 v[42:43], v[10:11]
	v_mov_b64_e32 v[40:41], v[8:9]
	v_mov_b64_e32 v[38:39], v[6:7]
	v_mov_b64_e32 v[36:37], v[4:5]
	v_mov_b64_e32 v[34:35], v[2:3]
	v_mov_b64_e32 v[30:31], v[14:15]
	v_mov_b64_e32 v[28:29], v[12:13]
	v_mov_b64_e32 v[26:27], v[10:11]
	v_mov_b64_e32 v[24:25], v[8:9]
	v_mov_b64_e32 v[22:23], v[6:7]
	v_mov_b64_e32 v[20:21], v[4:5]
	v_mov_b64_e32 v[18:19], v[2:3]
.LBB0_740:
	s_and_b32 s36, s17, 1
	s_add_i32 s17, s17, 1
	s_lshl_b32 s37, s36, 13
	s_cmp_lt_u32 s17, s22
	s_cbranch_scc0 .LBB0_744
	s_xor_b32 s47, s37, 0x2000
	s_add_i32 s47, s16, s47
	s_mov_b32 s50, s89
	s_mov_b32 s51, s90
	s_add_i32 m0, s47, 0x8000
	s_nop 0
	global_load_lds_dwordx4 v237, s[50:51]
.LBB0_744:
	v_add_u32_e32 v70, s37, v170
	ds_read_b128 v[66:69], v70 offset:0
	ds_read_b128 v[82:85], v70 offset:0x1000
	v_add_u32_e32 v71, s37, v171
	ds_read_b128 v[98:101], v71 offset:0
	ds_read_b128 v[102:105], v71 offset:0x1000
	s_waitcnt lgkmcnt(2)
	v_add_u32_e32 v114, s37, v172
	v_add_u32_e32 v115, s37, v173
	v_mfma_f32_32x32x16_bf16 v[66:81], v[66:69], v[130:133], 0
	ds_read_b128 v[106:109], v114 offset:0
	ds_read_b128 v[110:113], v114 offset:0x1000
	s_waitcnt lgkmcnt(2)
	v_mfma_f32_32x32x16_bf16 v[82:97], v[82:85], v[130:133], 0
	v_mfma_f32_32x32x16_bf16 v[66:81], v[98:101], v[134:137], v[66:81]
	ds_read_b128 v[98:101], v115 offset:0
	v_mfma_f32_32x32x16_bf16 v[82:97], v[102:105], v[134:137], v[82:97]
	ds_read_b128 v[102:105], v115 offset:0x1000
	s_waitcnt lgkmcnt(2)
	v_mfma_f32_32x32x16_bf16 v[66:81], v[106:109], v[138:141], v[66:81]
	s_waitcnt lgkmcnt(0)
	v_mfma_f32_32x32x16_bf16 v[82:97], v[110:113], v[138:141], v[82:97]
	v_mfma_f32_32x32x16_bf16 v[66:81], v[98:101], v[142:145], v[66:81]
	v_add_u32_e32 v194, s35, v176
	v_add_u32_e32 v98, 0xffffff21, v194
	s_movk_i32 s37, 0xfea2
	v_cmp_lt_u32_e32 vcc, s37, v98
	v_mfma_f32_32x32x16_bf16 v[82:97], v[102:105], v[142:145], v[82:97]
	s_and_saveexec_b64 s[50:51], vcc
	s_xor_b64 s[68:69], exec, s[50:51]
	s_cbranch_execz .LBB0_746
	s_mov_b32 s94, 2
	s_mov_b32 s32, 1
	v_add_u32_e32 v122, s35, v175
	v_add_u32_e32 v98, 64, v122
	v_med3_i32 v99, v98, 0, v191
	v_max_i32_e32 v98, 0xffffffe0, v98
	v_add_u32_e32 v98, 32, v98
	v_min_u32_e32 v98, 0x100, v98
	v_lshl_add_u32 v100, v98, 2, s19
	v_add_u32_e32 v98, 0x41, v122
	v_med3_i32 v101, v98, 0, v191
	v_max_i32_e32 v98, 0xffffffe0, v98
	v_add_u32_e32 v98, 32, v98
	v_min_u32_e32 v98, 0x100, v98
	v_lshl_add_u32 v102, v98, 2, s19
	v_add_u32_e32 v98, 0x42, v122
	v_med3_i32 v103, v98, 0, v191
	v_max_i32_e32 v98, 0xffffffe0, v98
	v_add_u32_e32 v98, 32, v98
	v_min_u32_e32 v98, 0x100, v98
	v_lshl_add_u32 v104, v98, 2, s19
	v_add_u32_e32 v98, 0x43, v122
	v_med3_i32 v105, v98, 0, v191
	v_max_i32_e32 v98, 0xffffffe0, v98
	v_add_u32_e32 v98, 32, v98
	v_min_u32_e32 v98, 0x100, v98
	v_lshl_add_u32 v99, v99, 2, s19
	v_lshl_add_u32 v101, v101, 2, s19
	v_lshl_add_u32 v103, v103, 2, s19
	v_lshl_add_u32 v105, v105, 2, s19
	v_lshl_add_u32 v106, v98, 2, s19
	ds_read_b32 v98, v99
	ds_read_b32 v100, v100
	ds_read_b32 v99, v101
	ds_read_b32 v101, v102
	ds_read_b32 v102, v103
	ds_read_b32 v104, v104
	ds_read_b32 v103, v105
	ds_read_b32 v105, v106
	v_add_u32_e32 v106, 0x48, v122
	v_med3_i32 v107, v106, 0, v191
	v_max_i32_e32 v106, 0xffffffe0, v106
	v_add_u32_e32 v106, 32, v106
	v_min_u32_e32 v106, 0x100, v106
	v_lshl_add_u32 v108, v106, 2, s19
	v_add_u32_e32 v106, 0x49, v122
	v_med3_i32 v109, v106, 0, v191
	v_max_i32_e32 v106, 0xffffffe0, v106
; template <int DQK, int MODE>
; DI void attn_body(const AttnArgs& a, char* lds) {
;     ...
;                 const int base = k0 - (qw0 + r32) + 4 * hi + 128;
; #pragma unroll
;                 for (int r = 0; r < 16; ++r) { const int i0 = base + (r & 3) + 8 * (r >> 2);
;                     const int j0 = min(max(i0, 0), 256), j1 = min(max(i0 + 32, 0), 256);
;                     p0[r] = fmaf(p0[r], C, a.tab[j0]); p1[r] = fmaf(p1[r], C, a.tab[j1]); }
;                 float pmax = p0[0];
; #pragma unroll
;                 for (int r = 1; r < 16; ++r) pmax = fmaxf(pmax, p0[r]);
; #pragma unroll
;                 for (int r = 0; r < 16; ++r) pmax = fmaxf(pmax, p1[r]);
;                 { auto rr = __builtin_amdgcn_permlane32_swap(__float_as_uint(pmax), __float_as_uint(pmax), false, false);
;                   pmax = fmaxf(__uint_as_float(rr[0]), __uint_as_float(rr[1])); }
;                 if (__builtin_expect(__all(pmax - m_reg <= THR_L2), 1)) { mn = m_reg; alpha = 1.f; }
;                 else { mn = fmaxf(m_reg, pmax); alpha = __builtin_amdgcn_exp2f(m_reg - mn); m_reg = mn; }
; #pragma unroll
;                 for (int r = 0; r < 16; ++r) { p0[r] -= mn; p1[r] -= mn; }
	v_add_u32_e32 v106, 32, v106
	v_min_u32_e32 v106, 0x100, v106
	v_lshl_add_u32 v110, v106, 2, s19
	v_add_u32_e32 v106, 0x4a, v122
	v_med3_i32 v111, v106, 0, v191
	v_max_i32_e32 v106, 0xffffffe0, v106
	v_add_u32_e32 v106, 32, v106
	v_min_u32_e32 v106, 0x100, v106
	v_lshl_add_u32 v112, v106, 2, s19
	v_add_u32_e32 v106, 0x4b, v122
	v_med3_i32 v113, v106, 0, v191
	v_max_i32_e32 v106, 0xffffffe0, v106
	v_add_u32_e32 v106, 32, v106
	v_min_u32_e32 v106, 0x100, v106
	v_lshl_add_u32 v107, v107, 2, s19
	v_lshl_add_u32 v109, v109, 2, s19
	v_lshl_add_u32 v111, v111, 2, s19
	v_lshl_add_u32 v113, v113, 2, s19
	v_lshl_add_u32 v114, v106, 2, s19
	ds_read_b32 v106, v107
	ds_read_b32 v108, v108
	ds_read_b32 v107, v109
	ds_read_b32 v109, v110
	ds_read_b32 v110, v111
	ds_read_b32 v112, v112
	ds_read_b32 v111, v113
	ds_read_b32 v113, v114
	v_add_u32_e32 v114, 0x50, v122
	v_med3_i32 v115, v114, 0, v191
	v_max_i32_e32 v114, 0xffffffe0, v114
	v_add_u32_e32 v114, 32, v114
	v_min_u32_e32 v114, 0x100, v114
	v_lshl_add_u32 v116, v114, 2, s19
	v_add_u32_e32 v114, 0x51, v122
	v_med3_i32 v117, v114, 0, v191
	v_max_i32_e32 v114, 0xffffffe0, v114
	v_add_u32_e32 v114, 32, v114
	v_min_u32_e32 v114, 0x100, v114
	v_lshl_add_u32 v118, v114, 2, s19
	v_add_u32_e32 v114, 0x52, v122
	v_med3_i32 v119, v114, 0, v191
	v_max_i32_e32 v114, 0xffffffe0, v114
	v_add_u32_e32 v114, 32, v114
	v_min_u32_e32 v114, 0x100, v114
	v_lshl_add_u32 v120, v114, 2, s19
	v_add_u32_e32 v114, 0x53, v122
	v_med3_i32 v121, v114, 0, v191
	v_max_i32_e32 v114, 0xffffffe0, v114
	v_add_u32_e32 v114, 32, v114
	v_min_u32_e32 v114, 0x100, v114
	v_lshl_add_u32 v115, v115, 2, s19
	v_lshl_add_u32 v117, v117, 2, s19
	v_lshl_add_u32 v119, v119, 2, s19
	v_lshl_add_u32 v121, v121, 2, s19
	v_lshl_add_u32 v123, v114, 2, s19
	ds_read_b32 v114, v115
	ds_read_b32 v116, v116
	ds_read_b32 v115, v117
	ds_read_b32 v117, v118
	ds_read_b32 v118, v119
	ds_read_b32 v120, v120
	ds_read_b32 v119, v121
	ds_read_b32 v121, v123
	v_add_u32_e32 v123, 0x58, v122
	v_add_u32_e32 v125, 0x59, v122
	v_add_u32_e32 v127, 0x5a, v122
	v_med3_i32 v124, v123, 0, v191
	v_max_i32_e32 v123, 0xffffffe0, v123
	v_med3_i32 v126, v125, 0, v191
	v_max_i32_e32 v125, 0xffffffe0, v125
	v_med3_i32 v128, v127, 0, v191
	v_max_i32_e32 v127, 0xffffffe0, v127
	v_add_u32_e32 v122, 0x5b, v122
	v_add_u32_e32 v123, 32, v123
	v_add_u32_e32 v125, 32, v125
	v_add_u32_e32 v127, 32, v127
	v_med3_i32 v129, v122, 0, v191
	v_max_i32_e32 v122, 0xffffffe0, v122
	s_waitcnt lgkmcnt(0)
	v_pk_fma_f32 v[66:67], v[66:67], s[44:45], v[98:99] op_sel_hi:[1,0,1]
	v_min_u32_e32 v123, 0x100, v123
	v_min_u32_e32 v125, 0x100, v125
	v_min_u32_e32 v127, 0x100, v127
	v_add_u32_e32 v122, 32, v122
	v_max_f32_e32 v98, v66, v67
	v_pk_fma_f32 v[68:69], v[68:69], s[44:45], v[102:103] op_sel_hi:[1,0,1]
	v_lshl_add_u32 v124, v124, 2, s19
	v_lshl_add_u32 v123, v123, 2, s19
	v_lshl_add_u32 v126, v126, 2, s19
	v_lshl_add_u32 v125, v125, 2, s19
	v_lshl_add_u32 v128, v128, 2, s19
	v_lshl_add_u32 v127, v127, 2, s19
	v_min_u32_e32 v122, 0x100, v122
	v_lshl_add_u32 v129, v129, 2, s19
	v_max3_f32 v98, v98, v68, v69
	v_pk_fma_f32 v[70:71], v[70:71], s[44:45], v[106:107] op_sel_hi:[1,0,1]
	v_lshl_add_u32 v179, v122, 2, s19
	ds_read_b32 v122, v124
	ds_read_b32 v124, v123
	ds_read_b32 v123, v126
	ds_read_b32 v125, v125
	ds_read_b32 v126, v128
	ds_read_b32 v128, v127
	ds_read_b32 v127, v129
	ds_read_b32 v129, v179
	v_max3_f32 v98, v98, v70, v71
	v_pk_fma_f32 v[72:73], v[72:73], s[44:45], v[110:111] op_sel_hi:[1,0,1]
	v_pk_fma_f32 v[74:75], v[74:75], s[44:45], v[114:115] op_sel_hi:[1,0,1]
	v_max3_f32 v98, v98, v72, v73
	v_max3_f32 v98, v98, v74, v75
	v_pk_fma_f32 v[76:77], v[76:77], s[44:45], v[118:119] op_sel_hi:[1,0,1]
	s_waitcnt lgkmcnt(0)
	v_pk_fma_f32 v[78:79], v[78:79], s[44:45], v[122:123] op_sel_hi:[1,0,1]
	v_max3_f32 v98, v98, v76, v77
	v_max3_f32 v98, v98, v78, v79
	v_pk_fma_f32 v[80:81], v[80:81], s[44:45], v[126:127] op_sel_hi:[1,0,1]
	v_pk_fma_f32 v[82:83], v[82:83], s[44:45], v[100:101] op_sel_hi:[1,0,1]
	v_max3_f32 v98, v98, v80, v81
	v_pk_fma_f32 v[84:85], v[84:85], s[44:45], v[104:105] op_sel_hi:[1,0,1]
	v_max3_f32 v98, v98, v82, v83
	v_pk_fma_f32 v[86:87], v[86:87], s[44:45], v[108:109] op_sel_hi:[1,0,1]
	v_max3_f32 v98, v98, v84, v85
	v_pk_fma_f32 v[88:89], v[88:89], s[44:45], v[112:113] op_sel_hi:[1,0,1]
	v_max3_f32 v98, v98, v86, v87
	v_pk_fma_f32 v[90:91], v[90:91], s[44:45], v[116:117] op_sel_hi:[1,0,1]
	v_max3_f32 v98, v98, v88, v89
	v_pk_fma_f32 v[92:93], v[92:93], s[44:45], v[120:121] op_sel_hi:[1,0,1]
	v_max3_f32 v98, v98, v90, v91
	v_pk_fma_f32 v[94:95], v[94:95], s[44:45], v[124:125] op_sel_hi:[1,0,1]
	v_max3_f32 v98, v98, v92, v93
	v_pk_fma_f32 v[96:97], v[96:97], s[44:45], v[128:129] op_sel_hi:[1,0,1]
	v_max3_f32 v98, v98, v94, v95
	v_max3_f32 v98, v98, v96, v97
	v_mov_b32_e32 v99, v98
	s_nop 1
	v_permlane32_swap_b32_e32 v98, v99
	v_max_f32_e32 v99, v99, v99
	v_max_f32_e32 v98, v98, v98
	v_max_f32_e32 v98, v98, v99
	v_sub_f32_e32 v99, v98, v177
	v_cmp_ge_f32_e32 vcc, s97, v99
	v_max_f32_e32 v99, v177, v177
	v_max_f32_e32 v98, v99, v98
	v_sub_f32_e32 v99, v177, v98
	v_exp_f32_e32 v99, v99
	s_cmp_eq_u64 vcc, exec
	s_cselect_b64 vcc, -1, 0
	v_cndmask_b32_e32 v177, v98, v177, vcc
	v_cndmask_b32_e64 v179, v99, 1.0, vcc
	v_sub_f32_e32 v113, v81, v177
	v_sub_f32_e32 v112, v80, v177
	v_sub_f32_e32 v111, v79, v177
	v_sub_f32_e32 v110, v78, v177
	v_sub_f32_e32 v109, v77, v177
	v_sub_f32_e32 v108, v76, v177
	v_sub_f32_e32 v107, v75, v177
	v_sub_f32_e32 v106, v74, v177
	v_sub_f32_e32 v105, v73, v177
	v_sub_f32_e32 v104, v72, v177
	v_sub_f32_e32 v103, v71, v177
	v_sub_f32_e32 v102, v70, v177
	v_sub_f32_e32 v101, v69, v177
	v_sub_f32_e32 v100, v68, v177
	v_sub_f32_e32 v99, v67, v177
	v_sub_f32_e32 v98, v66, v177
	v_sub_f32_e32 v129, v97, v177
	v_sub_f32_e32 v128, v96, v177
	v_sub_f32_e32 v127, v95, v177
	v_sub_f32_e32 v126, v94, v177
	v_sub_f32_e32 v125, v93, v177
	v_sub_f32_e32 v124, v92, v177
	v_sub_f32_e32 v123, v91, v177
	v_sub_f32_e32 v122, v90, v177
	v_sub_f32_e32 v121, v89, v177
	v_sub_f32_e32 v120, v88, v177
	v_sub_f32_e32 v119, v87, v177
	v_sub_f32_e32 v118, v86, v177
	v_sub_f32_e32 v117, v85, v177
	v_sub_f32_e32 v116, v84, v177
	v_sub_f32_e32 v115, v83, v177
	v_sub_f32_e32 v114, v82, v177
; template <int DQK, int MODE>
; DI void attn_body(const AttnArgs& a, char* lds) {
;     ...
;             if (relmax <= -128 || relmin >= 128) {
;                 const float bc = a.tab[relmax <= -128 ? 0 : 256];
;                 float pmax = p0[0];
; #pragma unroll
;                 for (int r = 1; r < 16; ++r) pmax = fmaxf(pmax, p0[r]);
; #pragma unroll
;                 for (int r = 0; r < 16; ++r) pmax = fmaxf(pmax, p1[r]);
;                 { auto rr = __builtin_amdgcn_permlane32_swap(__float_as_uint(pmax), __float_as_uint(pmax), false, false);
;                   pmax = fmaxf(__uint_as_float(rr[0]), __uint_as_float(rr[1])); }
;                 pmax = fmaf(pmax, C, bc);
;                 if (__builtin_expect(__all(pmax - m_reg <= THR_L2), 1)) { mn = m_reg; alpha = 1.f; }
;                 else { mn = fmaxf(m_reg, pmax); alpha = __builtin_amdgcn_exp2f(m_reg - mn); m_reg = mn; }
;                 const float off = bc - mn;
; #pragma unroll
;                 for (int r = 0; r < 16; ++r) { p0[r] = fmaf(p0[r], C, off); p1[r] = fmaf(p1[r], C, off); }
;     ...
;     auto finishSM = [&](f32x16& p0, f32x16& p1, float alpha, bf16x8& pa0, bf16x8& pa1, bf16x8& pa2, bf16x8& pa3) {
; #pragma unroll
;         for (int r = 0; r < 16; ++r) p1[r] = __builtin_amdgcn_exp2f(p1[r]);
;         float ps = 0;
; #pragma unroll
;         for (int r = 0; r < 16; ++r) ps += p0[r];
; #pragma unroll
;         for (int r = 0; r < 16; ++r) ps += p1[r];
;         { auto rr = __builtin_amdgcn_permlane32_swap(__float_as_uint(ps), __float_as_uint(ps), false, false);
;           ps = __uint_as_float(rr[0]) + __uint_as_float(rr[1]); }
;         l_reg = l_reg * alpha + ps;
;     ...
;         PK4(p0, 0, pa0); PK4(p0, 8, pa1); PK4(p1, 0, pa2); PK4(p1, 8, pa3);
.LBB0_746:
	s_andn2_saveexec_b64 s[68:69], s[68:69]
	s_cbranch_execz .LBB0_748
	s_nop 1
	v_max_f32_e32 v99, v66, v67
	v_max3_f32 v99, v99, v68, v69
	v_max3_f32 v99, v99, v70, v71
	v_max3_f32 v99, v99, v72, v73
	v_max3_f32 v99, v99, v74, v75
	v_max3_f32 v99, v99, v76, v77
	v_max3_f32 v99, v99, v78, v79
	v_max3_f32 v99, v99, v80, v81
	v_max3_f32 v99, v99, v82, v83
	v_max3_f32 v99, v99, v84, v85
	v_max3_f32 v99, v99, v86, v87
	v_max3_f32 v99, v99, v88, v89
	v_max3_f32 v99, v99, v90, v91
	v_max3_f32 v99, v99, v92, v93
	v_max3_f32 v99, v99, v94, v95
	v_max3_f32 v99, v99, v96, v97
	v_mov_b32_e32 v100, v99
	s_add_i32 s37, s35, s93
	s_cmp_lt_i32 s37, 0xffffff82
	s_cselect_b32 s37, 0, 1
	v_permlane32_swap_b32_e32 v99, v100
	v_max_f32_e32 v99, v99, v100
	s_cmp_lg_u32 s37, s94
	s_cbranch_scc1 .Lfar_a_slow
	v_fmamk_f32 v100, v99, 0x3e38aa3b, v241
	v_sub_f32_e32 v100, v100, v177
	v_cmp_ge_f32_e32 vcc, s97, v100
	s_mov_b32 s32, 0
	s_cmp_eq_u64 vcc, exec
	s_cbranch_scc1 .Lfar_a_fast
.Lfar_a_slow:
	s_mov_b32 s94, s37
	s_cmp_eq_u32 s37, 0
	s_cselect_b64 vcc, -1, 0
	v_cndmask_b32_e32 v241, v239, v238, vcc
	v_fmamk_f32 v99, v99, 0x3e38aa3b, v241
	v_max_f32_e32 v99, v177, v99
	v_sub_f32_e32 v100, v177, v99
	v_exp_f32_e32 v100, v100
	v_mov_b32_e32 v177, v99
	v_sub_f32_e32 v240, v241, v177
	v_mov_b32_e32 v179, v100
	s_mov_b32 s32, 1
.Lfar_a_fast:
	v_pk_fma_f32 v[112:113], v[80:81], s[44:45], v[240:241] op_sel_hi:[1,0,0]
	v_pk_fma_f32 v[110:111], v[78:79], s[44:45], v[240:241] op_sel_hi:[1,0,0]
	v_pk_fma_f32 v[108:109], v[76:77], s[44:45], v[240:241] op_sel_hi:[1,0,0]
	v_pk_fma_f32 v[106:107], v[74:75], s[44:45], v[240:241] op_sel_hi:[1,0,0]
	v_pk_fma_f32 v[104:105], v[72:73], s[44:45], v[240:241] op_sel_hi:[1,0,0]
	v_pk_fma_f32 v[102:103], v[70:71], s[44:45], v[240:241] op_sel_hi:[1,0,0]
	v_pk_fma_f32 v[100:101], v[68:69], s[44:45], v[240:241] op_sel_hi:[1,0,0]
	v_pk_fma_f32 v[98:99], v[66:67], s[44:45], v[240:241] op_sel_hi:[1,0,0]
	v_pk_fma_f32 v[128:129], v[96:97], s[44:45], v[240:241] op_sel_hi:[1,0,0]
	v_pk_fma_f32 v[126:127], v[94:95], s[44:45], v[240:241] op_sel_hi:[1,0,0]
	v_pk_fma_f32 v[124:125], v[92:93], s[44:45], v[240:241] op_sel_hi:[1,0,0]
	v_pk_fma_f32 v[122:123], v[90:91], s[44:45], v[240:241] op_sel_hi:[1,0,0]
	v_pk_fma_f32 v[120:121], v[88:89], s[44:45], v[240:241] op_sel_hi:[1,0,0]
	v_pk_fma_f32 v[118:119], v[86:87], s[44:45], v[240:241] op_sel_hi:[1,0,0]
	v_pk_fma_f32 v[116:117], v[84:85], s[44:45], v[240:241] op_sel_hi:[1,0,0]
	v_pk_fma_f32 v[114:115], v[82:83], s[44:45], v[240:241] op_sel_hi:[1,0,0]
.LBB0_748:
	s_or_b64 exec, exec, s[68:69]
	s_waitcnt vmcnt(0)
	s_barrier
	s_cmp_lt_u32 s17, s22
	s_cbranch_scc0 .Lstg_a_nov
	s_lshl_b32 s46, s36, 14
	s_xor_b32 s46, s46, 0x4000
	s_add_i32 s46, s16, s46
	s_mov_b32 s50, s89
	s_mov_b32 s51, s90
	s_mov_b32 m0, s46
	s_nop 0
	global_load_lds_dwordx4 v235, s[50:51]
	s_add_i32 m0, s46, 0x2000
	s_nop 0
	global_load_lds_dwordx4 v236, s[50:51]
.Lstg_a_nov:
	s_nop 0
	v_exp_f32_e32 v66, v98
	v_exp_f32_e32 v67, v99
	v_exp_f32_e32 v68, v100
	v_exp_f32_e32 v69, v101
	v_exp_f32_e32 v70, v102
	v_add_f32_e32 v78, 0, v66
	v_exp_f32_e32 v71, v103
	v_add_f32_e32 v78, v67, v78
	v_exp_f32_e32 v72, v104
	v_add_f32_e32 v78, v68, v78
	v_exp_f32_e32 v73, v105
	v_add_f32_e32 v78, v69, v78
	v_exp_f32_e32 v74, v106
	v_add_f32_e32 v78, v70, v78
	v_exp_f32_e32 v75, v107
	v_add_f32_e32 v78, v71, v78
	v_exp_f32_e32 v76, v108
	v_add_f32_e32 v78, v72, v78
	v_exp_f32_e32 v77, v109
	v_add_f32_e32 v78, v73, v78
	v_exp_f32_e32 v84, v110
	v_add_f32_e32 v78, v74, v78
	v_exp_f32_e32 v85, v111
	v_add_f32_e32 v78, v75, v78
	v_exp_f32_e32 v86, v112
	v_add_f32_e32 v78, v76, v78
	v_exp_f32_e32 v87, v113
	v_add_f32_e32 v78, v77, v78
	v_exp_f32_e32 v88, v114
	v_add_f32_e32 v78, v84, v78
	v_exp_f32_e32 v89, v115
	v_add_f32_e32 v78, v85, v78
	v_exp_f32_e32 v90, v116
	v_add_f32_e32 v78, v86, v78
	v_exp_f32_e32 v91, v117
	v_add_f32_e32 v78, v87, v78
	v_exp_f32_e32 v92, v118
	v_add_f32_e32 v78, v88, v78
	v_exp_f32_e32 v93, v119
	v_add_f32_e32 v78, v89, v78
	v_exp_f32_e32 v94, v120
	v_add_f32_e32 v78, v90, v78
	v_exp_f32_e32 v95, v121
	v_add_f32_e32 v78, v91, v78
	v_exp_f32_e32 v96, v122
	v_add_f32_e32 v78, v92, v78
	v_exp_f32_e32 v97, v123
	v_add_f32_e32 v78, v93, v78
	v_exp_f32_e32 v98, v124
	v_add_f32_e32 v78, v94, v78
	v_exp_f32_e32 v99, v125
	v_add_f32_e32 v78, v95, v78
	v_exp_f32_e32 v100, v126
	v_add_f32_e32 v78, v96, v78
	v_exp_f32_e32 v101, v127
	v_add_f32_e32 v78, v97, v78
	v_exp_f32_e32 v102, v128
	v_add_f32_e32 v78, v98, v78
	v_exp_f32_e32 v103, v129
	v_add_f32_e32 v78, v99, v78
	v_add_f32_e32 v78, v100, v78
	v_add_f32_e32 v78, v101, v78
	v_add_f32_e32 v78, v102, v78
	v_add_f32_e32 v82, v103, v78
	v_mov_b32_e32 v83, v82
	v_cvt_pk_bf16_f32 v78, v66, v67
	v_cvt_pk_bf16_f32 v79, v68, v69
	v_cvt_pk_bf16_f32 v80, v70, v71
	v_cvt_pk_bf16_f32 v81, v72, v73
	v_cvt_pk_bf16_f32 v74, v74, v75
	v_cvt_pk_bf16_f32 v75, v76, v77
	v_cvt_pk_bf16_f32 v76, v84, v85
	v_cvt_pk_bf16_f32 v77, v86, v87
	v_cvt_pk_bf16_f32 v70, v88, v89
	v_cvt_pk_bf16_f32 v71, v90, v91
	v_cvt_pk_bf16_f32 v72, v92, v93
	v_cvt_pk_bf16_f32 v73, v94, v95
	v_cvt_pk_bf16_f32 v66, v96, v97
	v_cvt_pk_bf16_f32 v67, v98, v99
	v_cvt_pk_bf16_f32 v68, v100, v101
	v_cvt_pk_bf16_f32 v69, v102, v103
	s_nop 1
	v_permlane32_swap_b32_e32 v82, v83
	s_cmp_eq_u32 s32, 0
	s_cbranch_scc1 .LBB0_752
; #define SBAR() __builtin_amdgcn_sched_barrier(0)
; template <int N> DI void wait_lgkm() { asm volatile("s_waitcnt lgkmcnt(%0)" :: "i"(N) : "memory"); }
; #define RESC(al) do { if (__any((al) < 1.f)) { if (hi == 0) al_l[r32] = (al); asm volatile("s_waitcnt lgkmcnt(0)" ::: "memory"); \
;     _Pragma("unroll") for (int d = 0; d < 4; ++d) _Pragma("unroll") for (int r = 0; r < 16; ++r) o[d][r] *= al_l[crow(r, hi)]; } } while (0)
; DI void pv_d0(f32x16* o, int vb, bf16x8 pa0, bf16x8 pa1, bf16x8 pa2, bf16x8 pa3) {
;     s16x4 fa[8], fb[8];
;     v_rd8<0>(fa, vb);
;     v_rd8<1>(fb, vb); wait_lgkm<8>(); SBAR(); pv_mm(o, fa, pa0);
;     v_rd8<2>(fa, vb); wait_lgkm<8>(); SBAR(); pv_mm(o, fb, pa1);
;     v_rd8<3>(fb, vb); wait_lgkm<8>(); SBAR(); pv_mm(o, fa, pa2);
;     wait_lgkm<0>(); SBAR(); pv_mm(o, fb, pa3);
; }
; template <int DQK, int MODE>
; DI void attn_body(const AttnArgs& a, char* lds) {
;     ...
;         RESC(alpha);
;         pv_d0(o, vb0 + cur * SHM_V, pa0, pa1, pa2, pa3);
;         asm volatile("s_waitcnt vmcnt(0)" ::: "memory");
;         __syncthreads();
;     }
;     __builtin_amdgcn_s_setprio(0);
	s_and_saveexec_b64 s[68:69], s[0:1]
	ds_write_b32 v169, v179 offset:128
	s_or_b64 exec, exec, s[68:69]
	s_waitcnt lgkmcnt(0)
	v_add_u32_e32 v96, v168, v0
	ds_read_b128 v[84:87], v96 offset:224
	ds_read_b128 v[88:91], v96 offset:192
	ds_read_b128 v[92:95], v96 offset:160
	ds_read_b128 v[96:99], v96 offset:128
	s_waitcnt lgkmcnt(0)
	v_pk_mul_f32 v[14:15], v[14:15], v[84:85]
	v_pk_mul_f32 v[10:11], v[10:11], v[88:89]
	v_pk_mul_f32 v[6:7], v[6:7], v[92:93]
	v_pk_mul_f32 v[16:17], v[16:17], v[86:87]
	v_pk_mul_f32 v[12:13], v[12:13], v[90:91]
	v_pk_mul_f32 v[8:9], v[8:9], v[94:95]
	v_pk_mul_f32 v[4:5], v[4:5], v[98:99]
	v_pk_mul_f32 v[2:3], v[2:3], v[96:97]
	v_pk_mul_f32 v[62:63], v[62:63], v[84:85]
	v_pk_mul_f32 v[58:59], v[58:59], v[88:89]
	v_pk_mul_f32 v[54:55], v[54:55], v[92:93]
	v_pk_mul_f32 v[64:65], v[64:65], v[86:87]
	v_pk_mul_f32 v[60:61], v[60:61], v[90:91]
	v_pk_mul_f32 v[56:57], v[56:57], v[94:95]
	v_pk_mul_f32 v[52:53], v[52:53], v[98:99]
	v_pk_mul_f32 v[50:51], v[50:51], v[96:97]
	v_pk_mul_f32 v[46:47], v[46:47], v[84:85]
	v_pk_mul_f32 v[42:43], v[42:43], v[88:89]
	v_pk_mul_f32 v[38:39], v[38:39], v[92:93]
	v_pk_mul_f32 v[48:49], v[48:49], v[86:87]
	v_pk_mul_f32 v[44:45], v[44:45], v[90:91]
	v_pk_mul_f32 v[40:41], v[40:41], v[94:95]
	v_pk_mul_f32 v[36:37], v[36:37], v[98:99]
	v_pk_mul_f32 v[34:35], v[34:35], v[96:97]
	v_pk_mul_f32 v[30:31], v[30:31], v[84:85]
	v_pk_mul_f32 v[26:27], v[26:27], v[88:89]
	v_pk_mul_f32 v[22:23], v[22:23], v[92:93]
	v_pk_mul_f32 v[32:33], v[32:33], v[86:87]
	v_pk_mul_f32 v[28:29], v[28:29], v[90:91]
	v_pk_mul_f32 v[24:25], v[24:25], v[94:95]
	v_pk_mul_f32 v[20:21], v[20:21], v[98:99]
	v_pk_mul_f32 v[18:19], v[18:19], v[96:97]
	v_mul_f32_e32 v178, v178, v179
.LBB0_752:
	v_add_f32_e32 v82, v82, v83
	v_lshl_add_u32 v83, s36, 14, v174
	ds_read_b64_tr_b16 v[84:85], v83 offset:0
	ds_read_b64_tr_b16 v[86:87], v83 offset:0x800
	ds_read_b64_tr_b16 v[88:89], v83 offset:0x200
	ds_read_b64_tr_b16 v[90:91], v83 offset:0xa00
	ds_read_b64_tr_b16 v[92:93], v83 offset:0x400
	ds_read_b64_tr_b16 v[94:95], v83 offset:0xc00
	ds_read_b64_tr_b16 v[96:97], v83 offset:0x600
	ds_read_b64_tr_b16 v[98:99], v83 offset:0xe00
	ds_read_b64_tr_b16 v[100:101], v83 offset:0x1000
	ds_read_b64_tr_b16 v[102:103], v83 offset:0x1800
	ds_read_b64_tr_b16 v[104:105], v83 offset:0x1200
	ds_read_b64_tr_b16 v[106:107], v83 offset:0x1a00
	ds_read_b64_tr_b16 v[108:109], v83 offset:0x1400
	ds_read_b64_tr_b16 v[110:111], v83 offset:0x1c00
	ds_read_b64_tr_b16 v[112:113], v83 offset:0x1600
	ds_read_b64_tr_b16 v[114:115], v83 offset:0x1e00
	s_waitcnt lgkmcnt(8)
	v_add_f32_e32 v82, v82, v178
	v_mfma_f32_32x32x16_bf16 v[2:17], v[78:81], v[84:87], v[2:17]
	v_mfma_f32_32x32x16_bf16 v[50:65], v[78:81], v[88:91], v[50:65]
	v_mfma_f32_32x32x16_bf16 v[34:49], v[78:81], v[92:95], v[34:49]
	v_mfma_f32_32x32x16_bf16 v[18:33], v[78:81], v[96:99], v[18:33]
	ds_read_b64_tr_b16 v[78:79], v83 offset:0x2000
	ds_read_b64_tr_b16 v[80:81], v83 offset:0x2800
	ds_read_b64_tr_b16 v[84:85], v83 offset:0x2200
	ds_read_b64_tr_b16 v[86:87], v83 offset:0x2a00
	ds_read_b64_tr_b16 v[88:89], v83 offset:0x2400
	ds_read_b64_tr_b16 v[90:91], v83 offset:0x2c00
	ds_read_b64_tr_b16 v[92:93], v83 offset:0x2600
	ds_read_b64_tr_b16 v[94:95], v83 offset:0x2e00
	s_waitcnt lgkmcnt(8)
	v_mfma_f32_32x32x16_bf16 v[2:17], v[74:77], v[100:103], v[2:17]
	v_mfma_f32_32x32x16_bf16 v[50:65], v[74:77], v[104:107], v[50:65]
	v_mfma_f32_32x32x16_bf16 v[34:49], v[74:77], v[108:111], v[34:49]
	v_mfma_f32_32x32x16_bf16 v[18:33], v[74:77], v[112:115], v[18:33]
	ds_read_b64_tr_b16 v[74:75], v83 offset:0x3000
	ds_read_b64_tr_b16 v[76:77], v83 offset:0x3800
	ds_read_b64_tr_b16 v[96:97], v83 offset:0x3200
	ds_read_b64_tr_b16 v[98:99], v83 offset:0x3a00
	ds_read_b64_tr_b16 v[100:101], v83 offset:0x3400
	ds_read_b64_tr_b16 v[102:103], v83 offset:0x3c00
	ds_read_b64_tr_b16 v[104:105], v83 offset:0x3600
	ds_read_b64_tr_b16 v[106:107], v83 offset:0x3e00
	s_waitcnt lgkmcnt(8)
	v_mfma_f32_32x32x16_bf16 v[2:17], v[70:73], v[78:81], v[2:17]
	s_waitcnt lgkmcnt(0)
	v_mfma_f32_32x32x16_bf16 v[50:65], v[70:73], v[84:87], v[50:65]
	v_mfma_f32_32x32x16_bf16 v[34:49], v[70:73], v[88:91], v[34:49]
	v_mfma_f32_32x32x16_bf16 v[18:33], v[70:73], v[92:95], v[18:33]
	v_mfma_f32_32x32x16_bf16 v[2:17], v[66:69], v[74:77], v[2:17]
	s_waitcnt vmcnt(0)
	s_add_i32 s35, s35, 64
	s_add_u32 s89, s89, 0x170000
	s_addc_u32 s90, s90, 0
	s_cmp_eq_u32 s22, s17
	s_waitcnt vmcnt(0) lgkmcnt(0)
	s_barrier
	v_mfma_f32_32x32x16_bf16 v[50:65], v[66:69], v[96:99], v[50:65]
	v_mfma_f32_32x32x16_bf16 v[34:49], v[66:69], v[100:103], v[34:49]
	v_mfma_f32_32x32x16_bf16 v[18:33], v[66:69], v[104:107], v[18:33]
	s_cbranch_scc1 .LBB0_754
	v_mov_b32_e32 v178, v82
	s_branch .LBB0_740
.LBB0_754:
	s_setprio 0
	s_cmp_lt_u32 s16, 0x1000
	s_cbranch_scc1 .Lstg_a_epi
	s_barrier
; DI unsigned short f2bf(float f) { return (unsigned short)(cvtpk(f, f) & 0xffffu); }
; DI int crow(int r, int hi) { return (r & 3) + 8 * (r >> 2) + 4 * hi; }
; template <int DQK, int MODE>
; DI void attn_body(const AttnArgs& a, char* lds) {
;     ...
;     if (hi == 0) li_l[r32] = l_reg; asm volatile("s_waitcnt lgkmcnt(0)" ::: "memory");
;     char* ost = lds + wid * 8192;
; #pragma unroll
;     for (int r = 0; r < 16; ++r) { const int orow = crow(r, hi); const float rl = __builtin_amdgcn_rcpf(li_l[orow]);
; #pragma unroll
;         for (int d0 = 0; d0 < 4; ++d0) *(bf16_t*)(ost + orow * 256 + (d0 * 32 + r32) * 2) = f2bf(o[d0][r] * rl); }
.Lstg_a_epi:
	s_and_saveexec_b64 s[68:69], s[0:1]
	ds_write_b32 v169, v82
	s_or_b64 exec, exec, s[68:69]
	s_waitcnt lgkmcnt(0)
	v_add_u32_e32 v0, v168, v0
	ds_read_b32 v66, v0
	v_lshl_add_u32 v67, v164, 13, 0
	v_lshl_add_u32 v68, v165, 1, v67
	v_lshl_add_u32 v69, v166, 10, v68
	s_and_b64 vcc, exec, s[66:67]
	s_waitcnt lgkmcnt(0)
	v_rcp_f32_e32 v66, v66
	s_nop 0
	v_mul_f32_e32 v2, v2, v66
	v_cvt_pk_bf16_f32 v2, v2, v2
	v_mul_f32_e32 v50, v50, v66
	ds_write_b16 v69, v2
	v_cvt_pk_bf16_f32 v2, v50, v50
	v_mul_f32_e32 v34, v34, v66
	ds_write_b16 v69, v2 offset:64
	v_cvt_pk_bf16_f32 v2, v34, v34
	ds_write_b16 v69, v2 offset:128
	v_mul_f32_e32 v2, v18, v66
	v_cvt_pk_bf16_f32 v2, v2, v2
	ds_read_b32 v18, v0 offset:4
	ds_write_b16 v69, v2 offset:192
	v_lshl_add_u32 v34, v167, 8, v68
	s_waitcnt lgkmcnt(1)
	v_rcp_f32_e32 v18, v18
	s_nop 0
	v_mul_f32_e32 v2, v3, v18
	v_cvt_pk_bf16_f32 v2, v2, v2
	v_mul_f32_e32 v3, v51, v18
	ds_write_b16 v34, v2 offset:256
	v_cvt_pk_bf16_f32 v2, v3, v3
	ds_write_b16 v34, v2 offset:320
	v_mul_f32_e32 v2, v35, v18
	v_cvt_pk_bf16_f32 v2, v2, v2
	ds_write_b16 v34, v2 offset:384
	v_mul_f32_e32 v2, v19, v18
	v_cvt_pk_bf16_f32 v2, v2, v2
	ds_read_b32 v3, v0 offset:8
	ds_write_b16 v34, v2 offset:448
	s_waitcnt lgkmcnt(1)
	v_rcp_f32_e32 v3, v3
	s_nop 0
	v_mul_f32_e32 v2, v4, v3
	v_cvt_pk_bf16_f32 v2, v2, v2
	ds_write_b16 v34, v2 offset:512
	v_mul_f32_e32 v2, v52, v3
	v_cvt_pk_bf16_f32 v2, v2, v2
	ds_write_b16 v34, v2 offset:576
	v_mul_f32_e32 v2, v36, v3
	v_cvt_pk_bf16_f32 v2, v2, v2
	ds_write_b16 v34, v2 offset:640
	v_mul_f32_e32 v2, v20, v3
	v_cvt_pk_bf16_f32 v2, v2, v2
	ds_read_b32 v3, v0 offset:12
	ds_write_b16 v34, v2 offset:704
	v_lshrrev_b32_e32 v4, 1, v162
	s_waitcnt lgkmcnt(1)
	v_rcp_f32_e32 v3, v3
	s_nop 0
	v_mul_f32_e32 v2, v5, v3
	v_cvt_pk_bf16_f32 v2, v2, v2
	ds_write_b16 v34, v2 offset:768
	v_mul_f32_e32 v2, v53, v3
	v_cvt_pk_bf16_f32 v2, v2, v2
	ds_write_b16 v34, v2 offset:832
	v_mul_f32_e32 v2, v37, v3
	v_cvt_pk_bf16_f32 v2, v2, v2
	ds_write_b16 v34, v2 offset:896
	v_mul_f32_e32 v2, v21, v3
	v_cvt_pk_bf16_f32 v2, v2, v2
	ds_read_b32 v3, v0 offset:32
	ds_write_b16 v34, v2 offset:960
	s_waitcnt lgkmcnt(1)
	v_rcp_f32_e32 v3, v3
	s_nop 0
	v_mul_f32_e32 v2, v6, v3
	v_cvt_pk_bf16_f32 v2, v2, v2
	ds_write_b16 v34, v2 offset:2048
	v_mul_f32_e32 v2, v54, v3
	v_cvt_pk_bf16_f32 v2, v2, v2
	ds_write_b16 v34, v2 offset:2112
	v_mul_f32_e32 v2, v38, v3
	v_cvt_pk_bf16_f32 v2, v2, v2
	ds_write_b16 v34, v2 offset:2176
	v_mul_f32_e32 v2, v22, v3
	v_cvt_pk_bf16_f32 v2, v2, v2
	ds_read_b32 v3, v0 offset:36
	ds_write_b16 v34, v2 offset:2240
	v_and_b32_e32 v6, 1, v161
	s_waitcnt lgkmcnt(1)
	v_rcp_f32_e32 v3, v3
	s_nop 0
	v_mul_f32_e32 v2, v7, v3
	v_cvt_pk_bf16_f32 v2, v2, v2
	ds_write_b16 v34, v2 offset:2304
	v_mul_f32_e32 v2, v55, v3
	v_cvt_pk_bf16_f32 v2, v2, v2
	ds_write_b16 v34, v2 offset:2368
	v_mul_f32_e32 v2, v39, v3
	v_cvt_pk_bf16_f32 v2, v2, v2
	ds_write_b16 v34, v2 offset:2432
	v_mul_f32_e32 v2, v23, v3
	v_cvt_pk_bf16_f32 v2, v2, v2
	ds_read_b32 v3, v0 offset:40
	ds_write_b16 v34, v2 offset:2496
	s_waitcnt lgkmcnt(1)
	v_rcp_f32_e32 v3, v3
	s_nop 0
	v_mul_f32_e32 v2, v8, v3
	v_cvt_pk_bf16_f32 v2, v2, v2
	ds_write_b16 v34, v2 offset:2560
	v_mul_f32_e32 v2, v56, v3
	v_cvt_pk_bf16_f32 v2, v2, v2
	ds_write_b16 v34, v2 offset:2624
	v_mul_f32_e32 v2, v40, v3
	v_cvt_pk_bf16_f32 v2, v2, v2
	ds_write_b16 v34, v2 offset:2688
	v_mul_f32_e32 v2, v24, v3
	v_cvt_pk_bf16_f32 v2, v2, v2
	ds_read_b32 v3, v0 offset:44
	ds_write_b16 v34, v2 offset:2752
	s_waitcnt lgkmcnt(1)
	v_rcp_f32_e32 v3, v3
	s_nop 0
	v_mul_f32_e32 v2, v9, v3
	v_cvt_pk_bf16_f32 v2, v2, v2
	ds_write_b16 v34, v2 offset:2816
	v_mul_f32_e32 v2, v57, v3
	v_cvt_pk_bf16_f32 v2, v2, v2
	ds_write_b16 v34, v2 offset:2880
	v_mul_f32_e32 v2, v41, v3
	v_cvt_pk_bf16_f32 v2, v2, v2
	ds_write_b16 v34, v2 offset:2944
	v_mul_f32_e32 v2, v25, v3
	v_cvt_pk_bf16_f32 v2, v2, v2
	ds_read_b32 v3, v0 offset:64
	ds_write_b16 v34, v2 offset:3008
	s_waitcnt lgkmcnt(1)
;     DI void* gp(int i) const { return (void*)(__attribute__((address_space(1))) void*)ld(i); }
; DI unsigned short f2bf(float f) { return (unsigned short)(cvtpk(f, f) & 0xffffu); }
; DI int crow(int r, int hi) { return (r & 3) + 8 * (r >> 2) + 4 * hi; }
; template <int DQK, int MODE>
; DI void attn_body(const AttnArgs& a, char* lds) {
;     ...
;     for (int r = 0; r < 16; ++r) { const int orow = crow(r, hi); const float rl = __builtin_amdgcn_rcpf(li_l[orow]);
; #pragma unroll
;         for (int d0 = 0; d0 < 4; ++d0) *(bf16_t*)(ost + orow * 256 + (d0 * 32 + r32) * 2) = f2bf(o[d0][r] * rl); }
;     asm volatile("s_waitcnt lgkmcnt(0)" ::: "memory");
;     {
;         const int row = lane >> 1, hf = lane & 1;
;         bf16_t* gp = a.O + (size_t)(wid * 32 + row) * a.ldo + hf * 64;
;         const char* sp = ost + row * 256 + hf * 128;
;         if (MODE != 1 || a.map == 0) {
; #pragma unroll
;             for (int c = 0; c < 8; ++c) *(u32x4*)(gp + c * 8) = *(const u32x4*)(sp + c * 16);
;         } else {
;             float v[64]; float ss = 0.f;
; #pragma unroll
;             for (int c = 0; c < 8; ++c) { const u32x4 w2 = *(const u32x4*)(sp + c * 16); const u32x4 w1 = *(const u32x4*)(gp + c * 8);
	v_rcp_f32_e32 v3, v3
	s_nop 0
	v_mul_f32_e32 v2, v10, v3
	v_cvt_pk_bf16_f32 v2, v2, v2
	ds_write_b16 v34, v2 offset:4096
	v_mul_f32_e32 v2, v58, v3
	v_cvt_pk_bf16_f32 v2, v2, v2
	ds_write_b16 v34, v2 offset:4160
	v_mul_f32_e32 v2, v42, v3
	v_cvt_pk_bf16_f32 v2, v2, v2
	ds_write_b16 v34, v2 offset:4224
	v_mul_f32_e32 v2, v26, v3
	v_cvt_pk_bf16_f32 v2, v2, v2
	ds_read_b32 v3, v0 offset:68
	ds_write_b16 v34, v2 offset:4288
	s_waitcnt lgkmcnt(1)
	v_rcp_f32_e32 v3, v3
	s_nop 0
	v_mul_f32_e32 v2, v11, v3
	v_cvt_pk_bf16_f32 v2, v2, v2
	ds_write_b16 v34, v2 offset:4352
	v_mul_f32_e32 v2, v59, v3
	v_cvt_pk_bf16_f32 v2, v2, v2
	ds_write_b16 v34, v2 offset:4416
	v_mul_f32_e32 v2, v43, v3
	v_cvt_pk_bf16_f32 v2, v2, v2
	ds_write_b16 v34, v2 offset:4480
	v_mul_f32_e32 v2, v27, v3
	v_cvt_pk_bf16_f32 v2, v2, v2
	ds_read_b32 v3, v0 offset:72
	ds_write_b16 v34, v2 offset:4544
	s_waitcnt lgkmcnt(1)
	v_rcp_f32_e32 v3, v3
	s_nop 0
	v_mul_f32_e32 v2, v12, v3
	v_cvt_pk_bf16_f32 v2, v2, v2
	ds_write_b16 v34, v2 offset:4608
	v_mul_f32_e32 v2, v60, v3
	v_cvt_pk_bf16_f32 v2, v2, v2
	ds_write_b16 v34, v2 offset:4672
	v_mul_f32_e32 v2, v44, v3
	v_cvt_pk_bf16_f32 v2, v2, v2
	ds_write_b16 v34, v2 offset:4736
	v_mul_f32_e32 v2, v28, v3
	v_cvt_pk_bf16_f32 v2, v2, v2
	ds_read_b32 v3, v0 offset:76
	ds_write_b16 v34, v2 offset:4800
	s_waitcnt lgkmcnt(1)
	v_rcp_f32_e32 v3, v3
	s_nop 0
	v_mul_f32_e32 v2, v13, v3
	v_cvt_pk_bf16_f32 v2, v2, v2
	ds_write_b16 v34, v2 offset:4864
	v_mul_f32_e32 v2, v61, v3
	v_cvt_pk_bf16_f32 v2, v2, v2
	ds_write_b16 v34, v2 offset:4928
	v_mul_f32_e32 v2, v45, v3
	v_cvt_pk_bf16_f32 v2, v2, v2
	ds_write_b16 v34, v2 offset:4992
	v_mul_f32_e32 v2, v29, v3
	v_cvt_pk_bf16_f32 v2, v2, v2
	ds_read_b32 v3, v0 offset:96
	ds_write_b16 v34, v2 offset:5056
	s_waitcnt lgkmcnt(1)
	v_rcp_f32_e32 v3, v3
	s_nop 0
	v_mul_f32_e32 v2, v14, v3
	v_cvt_pk_bf16_f32 v2, v2, v2
	ds_write_b16 v34, v2 offset:6144
	v_mul_f32_e32 v2, v62, v3
	v_cvt_pk_bf16_f32 v2, v2, v2
	ds_write_b16 v34, v2 offset:6208
	v_mul_f32_e32 v2, v46, v3
	v_cvt_pk_bf16_f32 v2, v2, v2
	ds_write_b16 v34, v2 offset:6272
	v_mul_f32_e32 v2, v30, v3
	v_cvt_pk_bf16_f32 v2, v2, v2
	ds_read_b32 v3, v0 offset:100
	ds_write_b16 v34, v2 offset:6336
	s_waitcnt lgkmcnt(1)
	v_rcp_f32_e32 v3, v3
	s_nop 0
	v_mul_f32_e32 v2, v15, v3
	v_cvt_pk_bf16_f32 v2, v2, v2
	ds_write_b16 v34, v2 offset:6400
	v_mul_f32_e32 v2, v63, v3
	v_cvt_pk_bf16_f32 v2, v2, v2
	ds_write_b16 v34, v2 offset:6464
	v_mul_f32_e32 v2, v47, v3
	v_cvt_pk_bf16_f32 v2, v2, v2
	ds_write_b16 v34, v2 offset:6528
	v_mul_f32_e32 v2, v31, v3
	v_cvt_pk_bf16_f32 v2, v2, v2
	ds_read_b32 v3, v0 offset:104
	ds_write_b16 v34, v2 offset:6592
	s_waitcnt lgkmcnt(1)
	v_rcp_f32_e32 v3, v3
	s_nop 0
	v_mul_f32_e32 v2, v16, v3
	v_cvt_pk_bf16_f32 v2, v2, v2
	ds_write_b16 v34, v2 offset:6656
	v_mul_f32_e32 v2, v64, v3
	v_cvt_pk_bf16_f32 v2, v2, v2
	ds_write_b16 v34, v2 offset:6720
	v_mul_f32_e32 v2, v48, v3
	v_cvt_pk_bf16_f32 v2, v2, v2
	ds_write_b16 v34, v2 offset:6784
	v_mul_f32_e32 v2, v32, v3
	v_cvt_pk_bf16_f32 v2, v2, v2
	ds_read_b32 v0, v0 offset:108
	ds_write_b16 v34, v2 offset:6848
	s_waitcnt lgkmcnt(1)
	v_rcp_f32_e32 v0, v0
	s_nop 0
	v_mul_f32_e32 v2, v17, v0
	v_cvt_pk_bf16_f32 v2, v2, v2
	ds_write_b16 v34, v2 offset:6912
	v_mul_f32_e32 v2, v65, v0
	v_cvt_pk_bf16_f32 v2, v2, v2
	ds_write_b16 v34, v2 offset:6976
	v_mul_f32_e32 v2, v49, v0
	v_mul_f32_e32 v0, v33, v0
	v_cvt_pk_bf16_f32 v2, v2, v2
	ds_write_b16 v34, v2 offset:7040
	v_cvt_pk_bf16_f32 v0, v0, v0
	ds_write_b16 v34, v0 offset:7104
	v_or_b32_e32 v0, v163, v4
	v_mov_b64_e32 v[2:3], s[64:65]
	v_mad_i64_i32 v[2:3], s[0:1], v0, s23, v[2:3]
	v_lshlrev_b32_e32 v0, 7, v6
	v_lshl_add_u64 v[26:27], v[2:3], 0, v[0:1]
	v_lshl_add_u32 v2, v4, 8, v67
	s_waitcnt lgkmcnt(0)
	v_add_u32_e32 v0, v2, v0
	ds_read_b128 v[2:5], v0
	s_mov_b64 s[0:1], -1
	s_cbranch_vccnz .LBB0_758
	s_andn2_b64 vcc, exec, s[0:1]
	s_cbranch_vccnz .LBB0_736
	s_branch .LBB0_759

; #define SBAR() __builtin_amdgcn_sched_barrier(0)
; template <int I, int N, class F> DI void cfor(F&& f) { if constexpr (I < N) { f(std::integral_constant<int, I>{}); cfor<I + 1, N>(f); } }
; template <int OFF> DI void dsr128(bf16x8& r, int addr) { asm volatile("ds_read_b128 %0, %1 offset:%2" : "=&v"(r) : "v"(addr), "i"(OFF) : "memory"); }
; template <int N> DI void wait_lgkm() { asm volatile("s_waitcnt lgkmcnt(%0)" :: "i"(N) : "memory"); }
; template <int DQK, int MODE>
; DI void attn_body(const AttnArgs& a, char* lds) {
;     ...
;     auto qkt = [&](f32x16& p0, f32x16& p1, const int kofs) {
;         p0 = f32x16{}; p1 = f32x16{};
;         int kc[NB];
; #pragma unroll
;         for (int i = 0; i < NB; ++i) kc[i] = kb[i] + kofs;
;         bf16x8 fk[2][2]; bf16x8 fq[2];
;         auto rd = [&](auto ic) { constexpr int d0 = decltype(ic)::value; constexpr int sl = d0 & 1;
;             dsr128<(d0 / NB) * (NB * 32)>(fk[sl][0], kc[d0 % NB]); dsr128<(d0 / NB) * (NB * 32) + 32 * KROWB>(fk[sl][1], kc[d0 % NB]);
;             if constexpr (MODE == 2 && d0 >= NQR) dsr128<(d0 - NQR) * 1024>(fq[sl], qra); };
;         rd(std::integral_constant<int, 0>{});
;         cfor<0, ND0>([&](auto ic) { constexpr int d0 = decltype(ic)::value; constexpr int sl = d0 & 1;
;             if constexpr (d0 + 1 < ND0) { rd(std::integral_constant<int, d0 + 1>{}); wait_lgkm<(MODE == 2 && d0 + 1 >= NQR) ? 3 : 2>(); }
;             else wait_lgkm<0>();
;             SBAR();
;             bf16x8 qf; if constexpr (MODE == 2 && d0 >= NQR) qf = fq[sl]; else qf = qr[d0 < NQR ? d0 : 0];
;             p0 = __builtin_amdgcn_mfma_f32_32x32x16_bf16(fk[sl][0], qf, p0, 0, 0, 0);
;             p1 = __builtin_amdgcn_mfma_f32_32x32x16_bf16(fk[sl][1], qf, p1, 0, 0, 0); });
;     };
;     ...
;     DMA(0, 0); asm volatile("s_waitcnt vmcnt(0)" ::: "memory"); __syncthreads();
;     if (wid >= 4) __builtin_amdgcn_s_setprio(1);
; #pragma unroll 1
;     for (int j = 0; j < NT; ++j) {
;         const int cur = j & 1;
;         if (j + 1 < NT) DMA(cur ^ 1, (j + 1) * 64);
;         f32x16 p0, p1; float mn, alpha;
;         qkt(p0, p1, cur * SHM_K);
.Lprio_skip_2:
	s_or_b64 exec, exec, s[10:11]
	v_subrev_u32_e32 v220, s14, v116
	v_subrev_u32_e32 v221, s14, v120
	v_subrev_u32_e32 v222, s14, v124
	v_lshlrev_b32_e32 v223, 7, v118
	v_lshlrev_b32_e32 v224, 7, v122
	v_lshlrev_b32_e32 v225, 7, v126
	v_subrev_u32_e32 v226, s14, v128
	v_subrev_u32_e32 v227, s14, v130
	v_add_u32_e32 v220, v220, v223
	v_add_u32_e32 v221, v221, v224
	v_add_u32_e32 v222, v222, v225
	v_add_u32_e32 v226, 0x100, v226
	v_add_u32_e32 v227, 0x100, v227
	s_add_u32 s89, s14, 0x40000
	s_addc_u32 s90, s12, 0
	s_cmp_lt_u32 s16, 0x1000
	s_cbranch_scc0 .Lstg_c_pro
	s_barrier
.Lstg_c_pro:
	s_add_i32 s10, 0, 0x8000
	s_cmp_lg_u32 s10, -1
	v_mul_u32_u24_e32 v0, 0x180, v136
	v_lshlrev_b32_e32 v4, 3, v136
	s_cselect_b32 s10, s10, 0
	v_bitop3_b32 v4, v114, v4, s34 bitop3:0x78
	v_add_u32_e32 v0, s10, v0
	s_and_b64 s[4:5], s[4:5], exec
	v_add_u32_e32 v119, v4, v0
	v_xad_u32 v123, v4, 32, v0
	v_xad_u32 v127, v4, 64, v0
	v_xad_u32 v140, v4, s13, v0
	s_cselect_b32 s33, 0x80, 64
	v_and_b32_e32 v4, 0x3fffffc0, v133
	s_add_i32 s4, 0, 0x14000
	v_and_b32_e32 v3, 0x100, v3
	v_and_b32_e32 v0, 0xc0, v14
	v_lshl_add_u32 v115, v4, 2, s4
	v_lshlrev_b32_e32 v4, 1, v134
	s_cmp_lg_u32 0, -1
	v_and_b32_e32 v4, 32, v4
	v_or3_b32 v0, v0, v3, v2
	s_cselect_b32 s10, 0, 0
	v_mov_b32_e32 v14, v1
	v_mov_b32_e32 v15, v1
	v_add3_u32 v142, v4, s10, v0
	v_mov_b32_e32 v0, v1
	v_mov_b32_e32 v2, v1
	v_mov_b32_e32 v3, v1
	v_mov_b32_e32 v4, v1
	v_mov_b32_e32 v5, v1
	v_mov_b32_e32 v6, v1
	v_mov_b32_e32 v7, v1
	v_mov_b32_e32 v8, v1
	v_mov_b32_e32 v9, v1
	v_mov_b32_e32 v10, v1
	v_mov_b32_e32 v11, v1
	v_mov_b32_e32 v12, v1
	v_mov_b32_e32 v13, v1
	v_mov_b64_e32 v[64:65], v[14:15]
	v_mov_b64_e32 v[48:49], v[14:15]
	v_mov_b64_e32 v[32:33], v[14:15]
	v_mov_b64_e32 v[62:63], v[12:13]
	v_mov_b64_e32 v[60:61], v[10:11]
	v_mov_b64_e32 v[58:59], v[8:9]
	v_mov_b64_e32 v[56:57], v[6:7]
	v_mov_b64_e32 v[54:55], v[4:5]
	v_mov_b64_e32 v[52:53], v[2:3]
	v_mov_b64_e32 v[50:51], v[0:1]
	v_mov_b64_e32 v[46:47], v[12:13]
	v_mov_b64_e32 v[44:45], v[10:11]
	v_mov_b64_e32 v[42:43], v[8:9]
	v_mov_b64_e32 v[40:41], v[6:7]
	v_mov_b64_e32 v[38:39], v[4:5]
	v_mov_b64_e32 v[36:37], v[2:3]
	v_mov_b64_e32 v[34:35], v[0:1]
	v_mov_b64_e32 v[30:31], v[12:13]
	v_mov_b64_e32 v[28:29], v[10:11]
	v_mov_b64_e32 v[26:27], v[8:9]
	v_mov_b64_e32 v[24:25], v[6:7]
	v_mov_b64_e32 v[22:23], v[4:5]
	v_mov_b64_e32 v[20:21], v[2:3]
	v_mov_b64_e32 v[18:19], v[0:1]
	v_mov_b64_e32 v[16:17], v[14:15]
	s_mov_b32 s17, 0
	s_mov_b32 s20, 64
	v_cmp_gt_u32_e64 s[4:5], 32, v134
	v_lshl_add_u32 v141, v136, 2, v115
	v_mov_b32_e32 v143, 0xf149f2ca
	v_mov_b32_e32 v144, 0
	v_mov_b64_e32 v[14:15], v[12:13]
	v_mov_b64_e32 v[12:13], v[10:11]
	v_mov_b64_e32 v[10:11], v[8:9]
	v_mov_b64_e32 v[8:9], v[6:7]
	v_mov_b64_e32 v[6:7], v[4:5]
	v_mov_b64_e32 v[4:5], v[2:3]
	v_mov_b64_e32 v[2:3], v[0:1]
	s_and_b32 s35, s17, 1
	s_add_i32 s17, s17, 1
.LBB0_784:
	s_cmp_ge_u32 s17, s33
	s_cbranch_scc1 .Lstg_c_nok
	s_xor_b32 s10, s35, 1
	s_mulk_i32 s10, 0x6000
	s_add_i32 s36, s16, s10
	s_mov_b32 s10, s14
	s_mov_b32 s11, s12
	s_add_i32 m0, s36, 0x8000
	s_nop 0
	global_load_lds_dwordx4 v220, s[10:11]
	s_add_i32 m0, s36, 0xa000
	v_add_u32_e32 v220, v220, v223
	global_load_lds_dwordx4 v221, s[10:11]
	s_add_i32 m0, s36, 0xc000
	v_add_u32_e32 v221, v221, v224
	global_load_lds_dwordx4 v222, s[10:11]
	v_add_u32_e32 v222, v222, v225
.Lstg_c_nok:
	s_mul_i32 s10, s35, 0x6000
	v_add_u32_e32 v0, s10, v119
	ds_read_b128 v[66:69], v0 offset:0
	ds_read_b128 v[70:73], v0 offset:0x3000
	v_add_u32_e32 v145, s10, v123
	ds_read_b128 v[146:149], v145 offset:0
	ds_read_b128 v[150:153], v145 offset:0x3000
	s_waitcnt lgkmcnt(2)
	v_add_u32_e32 v170, s10, v127
	v_add_u32_e32 v171, s10, v140
	v_mfma_f32_32x32x16_bf16 v[82:97], v[66:69], v[98:101], 0
	ds_read_b128 v[154:157], v170 offset:0
	ds_read_b128 v[158:161], v170 offset:0x3000
	s_waitcnt lgkmcnt(2)
	v_mfma_f32_32x32x16_bf16 v[66:81], v[70:73], v[98:101], 0
	v_mfma_f32_32x32x16_bf16 v[82:97], v[146:149], v[102:105], v[82:97]
	ds_read_b128 v[146:149], v171 offset:0
	v_mfma_f32_32x32x16_bf16 v[66:81], v[150:153], v[102:105], v[66:81]
	ds_read_b128 v[150:153], v171 offset:0x3000
	s_waitcnt lgkmcnt(2)
	v_mfma_f32_32x32x16_bf16 v[82:97], v[154:157], v[106:109], v[82:97]
	ds_read_b128 v[154:157], v0 offset:0x80
	v_mfma_f32_32x32x16_bf16 v[66:81], v[158:161], v[106:109], v[66:81]
	ds_read_b128 v[158:161], v0 offset:0x3080
	ds_read_b128 v[162:165], v139 offset:0
	s_waitcnt lgkmcnt(3)
	v_mfma_f32_32x32x16_bf16 v[82:97], v[146:149], v[110:113], v[82:97]
	ds_read_b128 v[146:149], v145 offset:0x80
	v_mfma_f32_32x32x16_bf16 v[66:81], v[150:153], v[110:113], v[66:81]
	ds_read_b128 v[150:153], v145 offset:0x3080
	ds_read_b128 v[166:169], v139 offset:0x400
	s_waitcnt lgkmcnt(3)
	v_mfma_f32_32x32x16_bf16 v[82:97], v[154:157], v[162:165], v[82:97]
	ds_read_b128 v[154:157], v170 offset:0x80
	v_mfma_f32_32x32x16_bf16 v[66:81], v[158:161], v[162:165], v[66:81]
	ds_read_b128 v[158:161], v170 offset:0x3080
	ds_read_b128 v[162:165], v139 offset:0x800
	s_waitcnt lgkmcnt(3)
	v_mfma_f32_32x32x16_bf16 v[82:97], v[146:149], v[166:169], v[82:97]
	ds_read_b128 v[146:149], v171 offset:0x80
	v_mfma_f32_32x32x16_bf16 v[66:81], v[150:153], v[166:169], v[66:81]
	ds_read_b128 v[150:153], v171 offset:0x3080
	ds_read_b128 v[166:169], v139 offset:0xc00
	s_waitcnt lgkmcnt(3)
	v_mfma_f32_32x32x16_bf16 v[82:97], v[154:157], v[162:165], v[82:97]
	ds_read_b128 v[154:157], v0 offset:0x100
	v_mfma_f32_32x32x16_bf16 v[66:81], v[158:161], v[162:165], v[66:81]
	ds_read_b128 v[158:161], v0 offset:0x3100
	ds_read_b128 v[162:165], v139 offset:0x1000
	s_waitcnt lgkmcnt(3)
; template <int DQK, int MODE>
; DI void attn_body(const AttnArgs& a, char* lds) {
;     ...
;             float pmax = p0[0];
; #pragma unroll
;             for (int r = 1; r < 16; ++r) pmax = fmaxf(pmax, p0[r]);
; #pragma unroll
;             for (int r = 0; r < 16; ++r) pmax = fmaxf(pmax, p1[r]);
;             { auto rr = __builtin_amdgcn_permlane32_swap(__float_as_uint(pmax), __float_as_uint(pmax), false, false);
;               pmax = fmaxf(__uint_as_float(rr[0]), __uint_as_float(rr[1])); }
;             if (__builtin_expect(__all((pmax - m_reg) * C <= THR_L2), 1)) { mn = m_reg; alpha = 1.f; }
;             else { mn = fmaxf(m_reg, pmax); alpha = __builtin_amdgcn_exp2f((m_reg - mn) * C); m_reg = mn; }
;             const float mnC = -mn * C;
; #pragma unroll
;             for (int r = 0; r < 16; ++r) { p0[r] = fmaf(p0[r], C, mnC); p1[r] = fmaf(p1[r], C, mnC); }
; #pragma unroll
;             for (int r = 0; r < 16; ++r) p0[r] = __builtin_amdgcn_exp2f(p0[r]);
;         }
;     };
;     auto finishSM = [&](f32x16& p0, f32x16& p1, float alpha, bf16x8& pa0, bf16x8& pa1, bf16x8& pa2, bf16x8& pa3) {
; #pragma unroll
;         for (int r = 0; r < 16; ++r) p1[r] = __builtin_amdgcn_exp2f(p1[r]);
;         float ps = 0;
; #pragma unroll
;         for (int r = 0; r < 16; ++r) ps += p0[r];
; #pragma unroll
;         for (int r = 0; r < 16; ++r) ps += p1[r];
;         { auto rr = __builtin_amdgcn_permlane32_swap(__float_as_uint(ps), __float_as_uint(ps), false, false);
;           ps = __uint_as_float(rr[0]) + __uint_as_float(rr[1]); }
;         l_reg = l_reg * alpha + ps;
;     ...
;         PK4(p0, 0, pa0); PK4(p0, 8, pa1); PK4(p1, 0, pa2); PK4(p1, 8, pa3);
	v_mfma_f32_32x32x16_bf16 v[82:97], v[146:149], v[166:169], v[82:97]
	ds_read_b128 v[146:149], v145 offset:0x100
	v_mfma_f32_32x32x16_bf16 v[66:81], v[150:153], v[166:169], v[66:81]
	ds_read_b128 v[150:153], v145 offset:0x3100
	ds_read_b128 v[166:169], v139 offset:0x1400
	s_waitcnt lgkmcnt(3)
	v_mfma_f32_32x32x16_bf16 v[82:97], v[154:157], v[162:165], v[82:97]
	ds_read_b128 v[154:157], v170 offset:0x100
	v_mfma_f32_32x32x16_bf16 v[66:81], v[158:161], v[162:165], v[66:81]
	ds_read_b128 v[158:161], v170 offset:0x3100
	ds_read_b128 v[162:165], v139 offset:0x1800
	s_waitcnt lgkmcnt(3)
	v_mfma_f32_32x32x16_bf16 v[82:97], v[146:149], v[166:169], v[82:97]
	ds_read_b128 v[146:149], v171 offset:0x100
	v_mfma_f32_32x32x16_bf16 v[66:81], v[150:153], v[166:169], v[66:81]
	ds_read_b128 v[150:153], v171 offset:0x3100
	ds_read_b128 v[166:169], v139 offset:0x1c00
	s_waitcnt lgkmcnt(3)
	v_mfma_f32_32x32x16_bf16 v[82:97], v[154:157], v[162:165], v[82:97]
	s_waitcnt lgkmcnt(0)
	v_mfma_f32_32x32x16_bf16 v[66:81], v[158:161], v[162:165], v[66:81]
	v_mfma_f32_32x32x16_bf16 v[82:97], v[146:149], v[166:169], v[82:97]
	v_mfma_f32_32x32x16_bf16 v[66:81], v[150:153], v[166:169], v[66:81]
	s_nop 9
	v_max_f32_e32 v145, v82, v83
	v_max3_f32 v145, v145, v84, v85
	v_max3_f32 v145, v145, v86, v87
	v_max3_f32 v145, v145, v88, v89
	v_max3_f32 v145, v145, v90, v91
	v_max3_f32 v145, v145, v92, v93
	v_max3_f32 v145, v145, v94, v95
	v_max3_f32 v145, v145, v96, v97
	v_max3_f32 v145, v145, v66, v67
	v_max3_f32 v145, v145, v68, v69
	v_max3_f32 v145, v145, v70, v71
	v_max3_f32 v145, v145, v72, v73
	v_max3_f32 v145, v145, v74, v75
	v_max3_f32 v145, v145, v76, v77
	v_max3_f32 v145, v145, v78, v79
	v_max3_f32 v145, v145, v80, v81
	v_mov_b32_e32 v146, v145
	s_nop 1
	v_permlane32_swap_b32_e32 v145, v146
	v_max_f32_e32 v145, v145, v146
	v_sub_f32_e32 v146, v145, v143
	v_cmp_ge_f32_e32 vcc, 0x42ddb3d8, v146
	s_mov_b32 s32, 0
	s_cmp_eq_u64 vcc, exec
	s_cbranch_scc1 .Ltrim_c_fast
	v_max_f32_e32 v0, v143, v145
	v_sub_f32_e32 v146, v143, v0
	v_mul_f32_e32 v146, 0x3dd53b94, v146
	v_exp_f32_e32 v146, v146
	v_mov_b32_e32 v143, v0
	v_mul_f32_e32 v241, 0xbdd53b94, v143
	v_mov_b32_e32 v0, v146
	s_mov_b32 s32, 1
.Ltrim_c_fast:
	v_fmamk_f32 v82, v82, 0x3dd53b94, v241
	v_fmamk_f32 v66, v66, 0x3dd53b94, v241
	v_fmamk_f32 v83, v83, 0x3dd53b94, v241
	v_fmamk_f32 v67, v67, 0x3dd53b94, v241
	v_fmamk_f32 v84, v84, 0x3dd53b94, v241
	v_fmamk_f32 v68, v68, 0x3dd53b94, v241
	v_fmamk_f32 v85, v85, 0x3dd53b94, v241
	v_fmamk_f32 v69, v69, 0x3dd53b94, v241
	v_fmamk_f32 v86, v86, 0x3dd53b94, v241
	v_fmamk_f32 v70, v70, 0x3dd53b94, v241
	v_fmamk_f32 v87, v87, 0x3dd53b94, v241
	v_fmamk_f32 v71, v71, 0x3dd53b94, v241
	v_fmamk_f32 v88, v88, 0x3dd53b94, v241
	v_fmamk_f32 v72, v72, 0x3dd53b94, v241
	v_fmamk_f32 v89, v89, 0x3dd53b94, v241
	v_fmamk_f32 v73, v73, 0x3dd53b94, v241
	v_fmamk_f32 v90, v90, 0x3dd53b94, v241
	v_fmamk_f32 v74, v74, 0x3dd53b94, v241
	v_fmamk_f32 v91, v91, 0x3dd53b94, v241
	v_fmamk_f32 v75, v75, 0x3dd53b94, v241
	v_fmamk_f32 v92, v92, 0x3dd53b94, v241
	v_fmamk_f32 v76, v76, 0x3dd53b94, v241
	v_fmamk_f32 v93, v93, 0x3dd53b94, v241
	v_fmamk_f32 v77, v77, 0x3dd53b94, v241
	v_fmamk_f32 v94, v94, 0x3dd53b94, v241
	v_fmamk_f32 v78, v78, 0x3dd53b94, v241
	v_fmamk_f32 v95, v95, 0x3dd53b94, v241
	v_fmamk_f32 v79, v79, 0x3dd53b94, v241
	v_fmamk_f32 v96, v96, 0x3dd53b94, v241
	v_fmamk_f32 v80, v80, 0x3dd53b94, v241
	v_fmamk_f32 v97, v97, 0x3dd53b94, v241
	v_fmamk_f32 v145, v81, 0x3dd53b94, v241
	s_waitcnt vmcnt(0)
	s_barrier
	s_cmp_ge_u32 s17, s33
	s_cbranch_scc1 .Lstg_c_nov
	s_lshl_b32 s10, s35, 14
	s_xor_b32 s10, s10, 0x4000
	s_add_i32 s46, s16, s10
	s_mov_b32 s10, s89
	s_mov_b32 s11, s90
	s_add_u32 s89, s89, 0x40000
	s_addc_u32 s90, s90, 0
	s_mov_b32 m0, s46
	s_nop 0
	global_load_lds_dwordx4 v226, s[10:11]
	s_add_i32 m0, s46, 0x2000
	s_nop 0
	global_load_lds_dwordx4 v227, s[10:11]
.Lstg_c_nov:
	v_exp_f32_e32 v81, v82
	v_exp_f32_e32 v146, v83
	v_exp_f32_e32 v84, v84
	v_exp_f32_e32 v85, v85
	v_exp_f32_e32 v86, v86
	v_exp_f32_e32 v147, v70
	v_add_f32_e32 v70, 0, v81
	v_exp_f32_e32 v87, v87
	v_add_f32_e32 v70, v146, v70
	v_exp_f32_e32 v88, v88
	v_add_f32_e32 v70, v84, v70
	v_exp_f32_e32 v89, v89
	v_add_f32_e32 v70, v85, v70
	v_exp_f32_e32 v90, v90
	v_add_f32_e32 v70, v86, v70
	v_exp_f32_e32 v91, v91
	v_add_f32_e32 v70, v87, v70
	v_exp_f32_e32 v92, v92
	v_add_f32_e32 v70, v88, v70
	v_exp_f32_e32 v93, v93
	v_add_f32_e32 v70, v89, v70
	v_exp_f32_e32 v94, v94
	v_add_f32_e32 v70, v90, v70
	v_exp_f32_e32 v95, v95
	v_add_f32_e32 v70, v91, v70
	v_exp_f32_e32 v96, v96
	v_add_f32_e32 v70, v92, v70
	v_exp_f32_e32 v97, v97
	v_add_f32_e32 v70, v93, v70
	v_exp_f32_e32 v66, v66
	v_add_f32_e32 v70, v94, v70
	v_exp_f32_e32 v67, v67
	v_add_f32_e32 v70, v95, v70
	v_exp_f32_e32 v68, v68
	v_add_f32_e32 v70, v96, v70
	v_exp_f32_e32 v69, v69
	v_add_f32_e32 v70, v97, v70
	v_add_f32_e32 v70, v66, v70
	v_exp_f32_e32 v148, v71
	v_add_f32_e32 v70, v67, v70
	v_exp_f32_e32 v149, v72
	v_add_f32_e32 v70, v68, v70
	v_exp_f32_e32 v73, v73
	v_add_f32_e32 v70, v69, v70
	v_exp_f32_e32 v150, v74
	v_add_f32_e32 v70, v147, v70
	v_exp_f32_e32 v151, v75
	v_add_f32_e32 v70, v148, v70
	v_exp_f32_e32 v152, v76
	v_add_f32_e32 v70, v149, v70
	v_exp_f32_e32 v153, v77
	v_add_f32_e32 v70, v73, v70
	v_exp_f32_e32 v154, v78
	v_add_f32_e32 v70, v150, v70
	v_exp_f32_e32 v155, v79
	v_add_f32_e32 v70, v151, v70
	v_exp_f32_e32 v156, v80
	v_add_f32_e32 v70, v152, v70
	v_exp_f32_e32 v145, v145
	v_add_f32_e32 v70, v153, v70
	v_add_f32_e32 v70, v154, v70
	v_add_f32_e32 v70, v155, v70
	v_add_f32_e32 v70, v156, v70
	v_add_f32_e32 v82, v145, v70
	v_mov_b32_e32 v83, v82
	v_cvt_pk_bf16_f32 v78, v81, v146
	v_cvt_pk_bf16_f32 v79, v84, v85
	v_cvt_pk_bf16_f32 v80, v86, v87
	v_cvt_pk_bf16_f32 v81, v88, v89
	v_cvt_pk_bf16_f32 v74, v90, v91
	v_cvt_pk_bf16_f32 v75, v92, v93
	v_cvt_pk_bf16_f32 v76, v94, v95
	v_cvt_pk_bf16_f32 v77, v96, v97
	v_cvt_pk_bf16_f32 v70, v66, v67
	v_cvt_pk_bf16_f32 v71, v68, v69
	v_cvt_pk_bf16_f32 v72, v147, v148
	v_cvt_pk_bf16_f32 v73, v149, v73
	v_cvt_pk_bf16_f32 v66, v150, v151
	v_cvt_pk_bf16_f32 v67, v152, v153
	v_cvt_pk_bf16_f32 v68, v154, v155
	v_cvt_pk_bf16_f32 v69, v156, v145
	s_nop 1
	v_permlane32_swap_b32_e32 v82, v83
	s_cmp_eq_u32 s32, 0
	s_cbranch_scc1 .LBB0_788
; #define SBAR() __builtin_amdgcn_sched_barrier(0)
; template <int N> DI void wait_lgkm() { asm volatile("s_waitcnt lgkmcnt(%0)" :: "i"(N) : "memory"); }
; #define RESC(al) do { if (__any((al) < 1.f)) { if (hi == 0) al_l[r32] = (al); asm volatile("s_waitcnt lgkmcnt(0)" ::: "memory"); \
;     _Pragma("unroll") for (int d = 0; d < 4; ++d) _Pragma("unroll") for (int r = 0; r < 16; ++r) o[d][r] *= al_l[crow(r, hi)]; } } while (0)
; DI void pv_d0(f32x16* o, int vb, bf16x8 pa0, bf16x8 pa1, bf16x8 pa2, bf16x8 pa3) {
;     s16x4 fa[8], fb[8];
;     v_rd8<0>(fa, vb);
;     v_rd8<1>(fb, vb); wait_lgkm<8>(); SBAR(); pv_mm(o, fa, pa0);
;     v_rd8<2>(fa, vb); wait_lgkm<8>(); SBAR(); pv_mm(o, fb, pa1);
;     v_rd8<3>(fb, vb); wait_lgkm<8>(); SBAR(); pv_mm(o, fa, pa2);
;     wait_lgkm<0>(); SBAR(); pv_mm(o, fb, pa3);
; }
; template <int DQK, int MODE>
; DI void attn_body(const AttnArgs& a, char* lds) {
;     ...
;         RESC(alpha);
;         pv_d0(o, vb0 + cur * SHM_V, pa0, pa1, pa2, pa3);
;         asm volatile("s_waitcnt vmcnt(0)" ::: "memory");
;         __syncthreads();
;     }
;     __builtin_amdgcn_s_setprio(0);
	s_and_saveexec_b64 s[10:11], s[4:5]
	ds_write_b32 v141, v0 offset:128
	s_or_b64 exec, exec, s[10:11]
	s_waitcnt lgkmcnt(0)
	v_add_u32_e32 v96, v115, v114
	ds_read_b128 v[84:87], v96 offset:224
	ds_read_b128 v[88:91], v96 offset:192
	ds_read_b128 v[92:95], v96 offset:160
	ds_read_b128 v[146:149], v96 offset:128
	s_waitcnt lgkmcnt(0)
	v_pk_mul_f32 v[62:63], v[62:63], v[84:85]
	v_pk_mul_f32 v[58:59], v[58:59], v[88:89]
	v_pk_mul_f32 v[54:55], v[54:55], v[92:93]
	v_pk_mul_f32 v[64:65], v[64:65], v[86:87]
	v_pk_mul_f32 v[60:61], v[60:61], v[90:91]
	v_pk_mul_f32 v[56:57], v[56:57], v[94:95]
	v_pk_mul_f32 v[52:53], v[52:53], v[148:149]
	v_pk_mul_f32 v[50:51], v[50:51], v[146:147]
	v_pk_mul_f32 v[46:47], v[46:47], v[84:85]
	v_pk_mul_f32 v[42:43], v[42:43], v[88:89]
	v_pk_mul_f32 v[38:39], v[38:39], v[92:93]
	v_pk_mul_f32 v[48:49], v[48:49], v[86:87]
	v_pk_mul_f32 v[44:45], v[44:45], v[90:91]
	v_pk_mul_f32 v[40:41], v[40:41], v[94:95]
	v_pk_mul_f32 v[36:37], v[36:37], v[148:149]
	v_pk_mul_f32 v[34:35], v[34:35], v[146:147]
	v_pk_mul_f32 v[30:31], v[30:31], v[84:85]
	v_pk_mul_f32 v[26:27], v[26:27], v[88:89]
	v_pk_mul_f32 v[22:23], v[22:23], v[92:93]
	v_pk_mul_f32 v[32:33], v[32:33], v[86:87]
	v_pk_mul_f32 v[28:29], v[28:29], v[90:91]
	v_pk_mul_f32 v[24:25], v[24:25], v[94:95]
	v_pk_mul_f32 v[20:21], v[20:21], v[148:149]
	v_pk_mul_f32 v[18:19], v[18:19], v[146:147]
	v_pk_mul_f32 v[14:15], v[14:15], v[84:85]
	v_pk_mul_f32 v[10:11], v[10:11], v[88:89]
	v_pk_mul_f32 v[6:7], v[6:7], v[92:93]
	v_pk_mul_f32 v[16:17], v[16:17], v[86:87]
	v_pk_mul_f32 v[12:13], v[12:13], v[90:91]
	v_pk_mul_f32 v[8:9], v[8:9], v[94:95]
	v_pk_mul_f32 v[4:5], v[4:5], v[148:149]
	v_pk_mul_f32 v[2:3], v[2:3], v[146:147]
	v_mul_f32_e32 v144, v144, v0
.LBB0_788:
	v_add_f32_e32 v82, v82, v83
	v_add_f32_e32 v82, v82, v144
	v_lshl_add_u32 v0, s35, 14, v142
	ds_read_b64_tr_b16 v[84:85], v0 offset:0
	ds_read_b64_tr_b16 v[86:87], v0 offset:0x800
	ds_read_b64_tr_b16 v[88:89], v0 offset:0x200
	ds_read_b64_tr_b16 v[90:91], v0 offset:0xa00
	ds_read_b64_tr_b16 v[92:93], v0 offset:0x400
	ds_read_b64_tr_b16 v[94:95], v0 offset:0xc00
	ds_read_b64_tr_b16 v[144:145], v0 offset:0x600
	ds_read_b64_tr_b16 v[146:147], v0 offset:0xe00
	ds_read_b64_tr_b16 v[148:149], v0 offset:0x1000
	ds_read_b64_tr_b16 v[150:151], v0 offset:0x1800
	ds_read_b64_tr_b16 v[152:153], v0 offset:0x1200
	ds_read_b64_tr_b16 v[154:155], v0 offset:0x1a00
	ds_read_b64_tr_b16 v[156:157], v0 offset:0x1400
	ds_read_b64_tr_b16 v[158:159], v0 offset:0x1c00
	ds_read_b64_tr_b16 v[160:161], v0 offset:0x1600
	ds_read_b64_tr_b16 v[162:163], v0 offset:0x1e00
	s_waitcnt lgkmcnt(8)
	s_nop 0
	v_mfma_f32_32x32x16_bf16 v[50:65], v[78:81], v[84:87], v[50:65]
	v_mfma_f32_32x32x16_bf16 v[34:49], v[78:81], v[88:91], v[34:49]
	v_mfma_f32_32x32x16_bf16 v[18:33], v[78:81], v[92:95], v[18:33]
	v_mfma_f32_32x32x16_bf16 v[2:17], v[78:81], v[144:147], v[2:17]
	ds_read_b64_tr_b16 v[78:79], v0 offset:0x2000
	ds_read_b64_tr_b16 v[80:81], v0 offset:0x2800
	ds_read_b64_tr_b16 v[84:85], v0 offset:0x2200
	ds_read_b64_tr_b16 v[86:87], v0 offset:0x2a00
	ds_read_b64_tr_b16 v[88:89], v0 offset:0x2400
	ds_read_b64_tr_b16 v[90:91], v0 offset:0x2c00
	ds_read_b64_tr_b16 v[92:93], v0 offset:0x2600
	ds_read_b64_tr_b16 v[94:95], v0 offset:0x2e00
	s_waitcnt lgkmcnt(8)
	v_mfma_f32_32x32x16_bf16 v[50:65], v[74:77], v[148:151], v[50:65]
	v_mfma_f32_32x32x16_bf16 v[34:49], v[74:77], v[152:155], v[34:49]
	v_mfma_f32_32x32x16_bf16 v[18:33], v[74:77], v[156:159], v[18:33]
	v_mfma_f32_32x32x16_bf16 v[2:17], v[74:77], v[160:163], v[2:17]
	ds_read_b64_tr_b16 v[74:75], v0 offset:0x3000
	ds_read_b64_tr_b16 v[76:77], v0 offset:0x3800
	ds_read_b64_tr_b16 v[144:145], v0 offset:0x3200
	ds_read_b64_tr_b16 v[146:147], v0 offset:0x3a00
	ds_read_b64_tr_b16 v[148:149], v0 offset:0x3400
	ds_read_b64_tr_b16 v[150:151], v0 offset:0x3c00
	ds_read_b64_tr_b16 v[152:153], v0 offset:0x3600
	ds_read_b64_tr_b16 v[154:155], v0 offset:0x3e00
	s_waitcnt lgkmcnt(8)
	v_mfma_f32_32x32x16_bf16 v[50:65], v[70:73], v[78:81], v[50:65]
	s_waitcnt lgkmcnt(0)
	v_mfma_f32_32x32x16_bf16 v[34:49], v[70:73], v[84:87], v[34:49]
	v_mfma_f32_32x32x16_bf16 v[18:33], v[70:73], v[88:91], v[18:33]
	v_mfma_f32_32x32x16_bf16 v[2:17], v[70:73], v[92:95], v[2:17]
	v_mfma_f32_32x32x16_bf16 v[50:65], v[66:69], v[74:77], v[50:65]
	s_waitcnt vmcnt(0)
	s_add_i32 s20, s20, 64
	s_cmp_eq_u32 s33, s17
	s_waitcnt vmcnt(0) lgkmcnt(0)
	s_barrier
	v_mfma_f32_32x32x16_bf16 v[34:49], v[66:69], v[144:147], v[34:49]
	v_mfma_f32_32x32x16_bf16 v[18:33], v[66:69], v[148:151], v[18:33]
	v_mfma_f32_32x32x16_bf16 v[2:17], v[66:69], v[152:155], v[2:17]
	s_cbranch_scc1 .LBB0_790
	v_mov_b32_e32 v144, v82
	s_and_b32 s35, s17, 1
	s_add_i32 s17, s17, 1
	s_branch .LBB0_784

; template <int DQK, int MODE>
; DI void attn_body(const AttnArgs& a, char* lds) {
;     ...
;     if (hi == 0) li_l[r32] = l_reg; asm volatile("s_waitcnt lgkmcnt(0)" ::: "memory");
.Lstg_c_epi:
	s_and_saveexec_b64 s[10:11], s[4:5]
	s_cbranch_execz .LBB0_761
	ds_write_b32 v141, v82
	s_branch .LBB0_761

; #define SBAR() __builtin_amdgcn_sched_barrier(0)
; template <int N> DI void wait_lgkm() { asm volatile("s_waitcnt lgkmcnt(%0)" :: "i"(N) : "memory"); }
; template <int DQK, int MODE>
; DI void attn_body(const AttnArgs& a, char* lds) {
;     ...
;     auto qkt = [&](f32x16& p0, f32x16& p1, const int kofs) {
;         p0 = f32x16{}; p1 = f32x16{};
;         int kc[NB];
; #pragma unroll
;         for (int i = 0; i < NB; ++i) kc[i] = kb[i] + kofs;
;         bf16x8 fk[2][2]; bf16x8 fq[2];
;         auto rd = [&](auto ic) { constexpr int d0 = decltype(ic)::value; constexpr int sl = d0 & 1;
;             dsr128<(d0 / NB) * (NB * 32)>(fk[sl][0], kc[d0 % NB]); dsr128<(d0 / NB) * (NB * 32) + 32 * KROWB>(fk[sl][1], kc[d0 % NB]);
;             if constexpr (MODE == 2 && d0 >= NQR) dsr128<(d0 - NQR) * 1024>(fq[sl], qra); };
;         rd(std::integral_constant<int, 0>{});
;         cfor<0, ND0>([&](auto ic) { constexpr int d0 = decltype(ic)::value; constexpr int sl = d0 & 1;
;             if constexpr (d0 + 1 < ND0) { rd(std::integral_constant<int, d0 + 1>{}); wait_lgkm<(MODE == 2 && d0 + 1 >= NQR) ? 3 : 2>(); }
;             else wait_lgkm<0>();
;             SBAR();
;             bf16x8 qf; if constexpr (MODE == 2 && d0 >= NQR) qf = fq[sl]; else qf = qr[d0 < NQR ? d0 : 0];
;             p0 = __builtin_amdgcn_mfma_f32_32x32x16_bf16(fk[sl][0], qf, p0, 0, 0, 0);
;             p1 = __builtin_amdgcn_mfma_f32_32x32x16_bf16(fk[sl][1], qf, p1, 0, 0, 0); });
;     };
;     ...
;         } else {
;             float pmax = p0[0];
; #pragma unroll
;             for (int r = 1; r < 16; ++r) pmax = fmaxf(pmax, p0[r]);
; #pragma unroll
;             for (int r = 0; r < 16; ++r) pmax = fmaxf(pmax, p1[r]);
;             { auto rr = __builtin_amdgcn_permlane32_swap(__float_as_uint(pmax), __float_as_uint(pmax), false, false);
;               pmax = fmaxf(__uint_as_float(rr[0]), __uint_as_float(rr[1])); }
;             if (__builtin_expect(__all((pmax - m_reg) * C <= THR_L2), 1)) { mn = m_reg; alpha = 1.f; }
;             else { mn = fmaxf(m_reg, pmax); alpha = __builtin_amdgcn_exp2f((m_reg - mn) * C); m_reg = mn; }
;             const float mnC = -mn * C;
; #pragma unroll
;             for (int r = 0; r < 16; ++r) { p0[r] = fmaf(p0[r], C, mnC); p1[r] = fmaf(p1[r], C, mnC); }
; #pragma unroll
;             for (int r = 0; r < 16; ++r) p0[r] = __builtin_amdgcn_exp2f(p0[r]);
.LBB0_811:
	v_add_u32_e32 v74, s49, v145
	ds_read_b128 v[66:69], v74 offset:0
	ds_read_b128 v[70:73], v74 offset:0x2000
	v_add_u32_e32 v75, s49, v146
	ds_read_b128 v[158:161], v75 offset:0
	ds_read_b128 v[162:165], v75 offset:0x2000
	s_waitcnt lgkmcnt(2)
	v_add_u32_e32 v157, s49, v147
	v_add_u32_e32 v174, s49, v148
	v_add_u32_e32 v175, s49, v150
	v_add_u32_e32 v176, s49, v151
	v_add_u32_e32 v177, s49, v152
	v_add_u32_e32 v178, s49, v153
	v_mfma_f32_32x32x16_bf16 v[82:97], v[66:69], v[98:101], 0
	ds_read_b128 v[166:169], v157 offset:0
	ds_read_b128 v[170:173], v157 offset:0x2000
	s_waitcnt lgkmcnt(2)
	v_mfma_f32_32x32x16_bf16 v[66:81], v[70:73], v[98:101], 0
	v_mfma_f32_32x32x16_bf16 v[82:97], v[158:161], v[102:105], v[82:97]
	ds_read_b128 v[158:161], v174 offset:0
	v_mfma_f32_32x32x16_bf16 v[66:81], v[162:165], v[102:105], v[66:81]
	ds_read_b128 v[162:165], v174 offset:0x2000
	s_waitcnt lgkmcnt(2)
	v_mfma_f32_32x32x16_bf16 v[82:97], v[166:169], v[106:109], v[82:97]
	ds_read_b128 v[166:169], v175 offset:0
	v_mfma_f32_32x32x16_bf16 v[66:81], v[170:173], v[106:109], v[66:81]
	ds_read_b128 v[170:173], v175 offset:0x2000
	s_waitcnt lgkmcnt(2)
	v_mfma_f32_32x32x16_bf16 v[82:97], v[158:161], v[110:113], v[82:97]
	ds_read_b128 v[158:161], v176 offset:0
	v_mfma_f32_32x32x16_bf16 v[66:81], v[162:165], v[110:113], v[66:81]
	ds_read_b128 v[162:165], v176 offset:0x2000
	s_waitcnt lgkmcnt(2)
	v_mfma_f32_32x32x16_bf16 v[82:97], v[166:169], v[114:117], v[82:97]
	ds_read_b128 v[166:169], v177 offset:0
	v_mfma_f32_32x32x16_bf16 v[66:81], v[170:173], v[114:117], v[66:81]
	ds_read_b128 v[170:173], v177 offset:0x2000
	s_waitcnt lgkmcnt(2)
	v_mfma_f32_32x32x16_bf16 v[82:97], v[158:161], v[118:121], v[82:97]
	ds_read_b128 v[158:161], v178 offset:0
	v_mfma_f32_32x32x16_bf16 v[66:81], v[162:165], v[118:121], v[66:81]
	ds_read_b128 v[162:165], v178 offset:0x2000
	s_waitcnt lgkmcnt(2)
	v_mfma_f32_32x32x16_bf16 v[82:97], v[166:169], v[122:125], v[82:97]
	s_waitcnt lgkmcnt(0)
	v_mfma_f32_32x32x16_bf16 v[66:81], v[170:173], v[122:125], v[66:81]
	v_mfma_f32_32x32x16_bf16 v[82:97], v[158:161], v[126:129], v[82:97]
	v_mfma_f32_32x32x16_bf16 v[66:81], v[162:165], v[126:129], v[66:81]
	s_nop 9
	v_max_f32_e32 v158, v82, v83
	v_max3_f32 v158, v158, v84, v85
	v_max3_f32 v158, v158, v86, v87
	v_max3_f32 v158, v158, v88, v89
	v_max3_f32 v158, v158, v90, v91
	v_max3_f32 v158, v158, v92, v93
	v_max3_f32 v158, v158, v94, v95
	v_max3_f32 v158, v158, v96, v97
	v_max3_f32 v158, v158, v66, v67
	v_max3_f32 v158, v158, v68, v69
	v_max3_f32 v158, v158, v70, v71
	v_max3_f32 v158, v158, v72, v73
	v_max3_f32 v158, v158, v74, v75
	v_max3_f32 v158, v158, v76, v77
	v_max3_f32 v158, v158, v78, v79
	v_max3_f32 v158, v158, v80, v81
	v_mov_b32_e32 v159, v158
	s_nop 1
	v_permlane32_swap_b32_e32 v158, v159
	v_max_f32_e32 v158, v158, v159
	v_sub_f32_e32 v159, v158, v155
	v_cmp_ge_f32_e32 vcc, 0x42b504f3, v159
	s_mov_b32 s32, 0
	s_cmp_eq_u64 vcc, exec
	s_cbranch_scc1 .Ltrim_b_fast
	v_max_f32_e32 v157, v155, v158
	v_sub_f32_e32 v159, v155, v157
	v_mul_f32_e32 v159, 0x3e0293ee, v159
	v_exp_f32_e32 v159, v159
	v_mov_b32_e32 v155, v157
	v_mul_f32_e32 v241, 0xbe0293ee, v155
	v_mov_b32_e32 v157, v159
	s_mov_b32 s32, 1
.Ltrim_b_fast:
	v_fmamk_f32 v82, v82, 0x3e0293ee, v241
	v_fmamk_f32 v66, v66, 0x3e0293ee, v241
	v_fmamk_f32 v83, v83, 0x3e0293ee, v241
	v_fmamk_f32 v67, v67, 0x3e0293ee, v241
	v_fmamk_f32 v84, v84, 0x3e0293ee, v241
	v_fmamk_f32 v68, v68, 0x3e0293ee, v241
	v_fmamk_f32 v85, v85, 0x3e0293ee, v241
	v_fmamk_f32 v69, v69, 0x3e0293ee, v241
	v_fmamk_f32 v86, v86, 0x3e0293ee, v241
	v_fmamk_f32 v70, v70, 0x3e0293ee, v241
	v_fmamk_f32 v87, v87, 0x3e0293ee, v241
	v_fmamk_f32 v71, v71, 0x3e0293ee, v241
	v_fmamk_f32 v88, v88, 0x3e0293ee, v241
	v_fmamk_f32 v72, v72, 0x3e0293ee, v241
	v_fmamk_f32 v89, v89, 0x3e0293ee, v241
	v_fmamk_f32 v73, v73, 0x3e0293ee, v241
	v_fmamk_f32 v90, v90, 0x3e0293ee, v241
	v_fmamk_f32 v74, v74, 0x3e0293ee, v241
	v_fmamk_f32 v91, v91, 0x3e0293ee, v241
	v_fmamk_f32 v75, v75, 0x3e0293ee, v241
	v_fmamk_f32 v92, v92, 0x3e0293ee, v241
	v_fmamk_f32 v76, v76, 0x3e0293ee, v241
	v_fmamk_f32 v93, v93, 0x3e0293ee, v241
	v_fmamk_f32 v77, v77, 0x3e0293ee, v241
	v_fmamk_f32 v94, v94, 0x3e0293ee, v241
	v_fmamk_f32 v78, v78, 0x3e0293ee, v241
	v_fmamk_f32 v95, v95, 0x3e0293ee, v241
	v_fmamk_f32 v79, v79, 0x3e0293ee, v241
	v_fmamk_f32 v96, v96, 0x3e0293ee, v241
	v_fmamk_f32 v80, v80, 0x3e0293ee, v241
	v_fmamk_f32 v97, v97, 0x3e0293ee, v241
	v_fmamk_f32 v158, v81, 0x3e0293ee, v241
	s_waitcnt vmcnt(0)
	s_barrier
	s_cmp_lt_u32 s36, s47
	s_cbranch_scc0 .Lstg_b_nov
	s_xor_b32 s46, s49, 0x4000
	s_add_i32 s46, s35, s46
	s_mov_b32 s52, s89
	s_mov_b32 s53, s90
	s_mov_b32 m0, s46
	s_nop 0
	global_load_lds_dwordx4 v216, s[52:53]
	s_add_i32 m0, s46, 0x2000
	s_nop 0
	global_load_lds_dwordx4 v217, s[52:53]
; template <int DQK, int MODE>
; DI void attn_body(const AttnArgs& a, char* lds) {
;     ...
;     auto finishSM = [&](f32x16& p0, f32x16& p1, float alpha, bf16x8& pa0, bf16x8& pa1, bf16x8& pa2, bf16x8& pa3) {
; #pragma unroll
;         for (int r = 0; r < 16; ++r) p1[r] = __builtin_amdgcn_exp2f(p1[r]);
;         float ps = 0;
; #pragma unroll
;         for (int r = 0; r < 16; ++r) ps += p0[r];
; #pragma unroll
;         for (int r = 0; r < 16; ++r) ps += p1[r];
;         { auto rr = __builtin_amdgcn_permlane32_swap(__float_as_uint(ps), __float_as_uint(ps), false, false);
;           ps = __uint_as_float(rr[0]) + __uint_as_float(rr[1]); }
;         l_reg = l_reg * alpha + ps;
;     ...
;         PK4(p0, 0, pa0); PK4(p0, 8, pa1); PK4(p1, 0, pa2); PK4(p1, 8, pa3);
.Lstg_b_nov:
	v_exp_f32_e32 v81, v82
	v_exp_f32_e32 v159, v83
	v_exp_f32_e32 v84, v84
	v_exp_f32_e32 v85, v85
	v_exp_f32_e32 v86, v86
	v_exp_f32_e32 v160, v70
	v_add_f32_e32 v70, 0, v81
	v_exp_f32_e32 v87, v87
	v_add_f32_e32 v70, v159, v70
	v_exp_f32_e32 v88, v88
	v_add_f32_e32 v70, v84, v70
	v_exp_f32_e32 v89, v89
	v_add_f32_e32 v70, v85, v70
	v_exp_f32_e32 v90, v90
	v_add_f32_e32 v70, v86, v70
	v_exp_f32_e32 v91, v91
	v_add_f32_e32 v70, v87, v70
	v_exp_f32_e32 v92, v92
	v_add_f32_e32 v70, v88, v70
	v_exp_f32_e32 v93, v93
	v_add_f32_e32 v70, v89, v70
	v_exp_f32_e32 v94, v94
	v_add_f32_e32 v70, v90, v70
	v_exp_f32_e32 v95, v95
	v_add_f32_e32 v70, v91, v70
	v_exp_f32_e32 v96, v96
	v_add_f32_e32 v70, v92, v70
	v_exp_f32_e32 v97, v97
	v_add_f32_e32 v70, v93, v70
	v_exp_f32_e32 v66, v66
	v_add_f32_e32 v70, v94, v70
	v_exp_f32_e32 v67, v67
	v_add_f32_e32 v70, v95, v70
	v_exp_f32_e32 v68, v68
	v_add_f32_e32 v70, v96, v70
	v_exp_f32_e32 v69, v69
	v_add_f32_e32 v70, v97, v70
	v_add_f32_e32 v70, v66, v70
	v_exp_f32_e32 v161, v71
	v_add_f32_e32 v70, v67, v70
	v_exp_f32_e32 v162, v72
	v_add_f32_e32 v70, v68, v70
	v_exp_f32_e32 v73, v73
	v_add_f32_e32 v70, v69, v70
	v_exp_f32_e32 v163, v74
	v_add_f32_e32 v70, v160, v70
	v_exp_f32_e32 v164, v75
	v_add_f32_e32 v70, v161, v70
	v_exp_f32_e32 v165, v76
	v_add_f32_e32 v70, v162, v70
	v_exp_f32_e32 v166, v77
	v_add_f32_e32 v70, v73, v70
	v_exp_f32_e32 v167, v78
	v_add_f32_e32 v70, v163, v70
	v_exp_f32_e32 v168, v79
	v_add_f32_e32 v70, v164, v70
	v_exp_f32_e32 v169, v80
	v_add_f32_e32 v70, v165, v70
	v_exp_f32_e32 v158, v158
	v_add_f32_e32 v70, v166, v70
	v_add_f32_e32 v70, v167, v70
	v_add_f32_e32 v70, v168, v70
	v_add_f32_e32 v70, v169, v70
	v_add_f32_e32 v82, v158, v70
	v_mov_b32_e32 v83, v82
	v_cvt_pk_bf16_f32 v78, v81, v159
	v_cvt_pk_bf16_f32 v79, v84, v85
	v_cvt_pk_bf16_f32 v80, v86, v87
	v_cvt_pk_bf16_f32 v81, v88, v89
	v_cvt_pk_bf16_f32 v74, v90, v91
	v_cvt_pk_bf16_f32 v75, v92, v93
	v_cvt_pk_bf16_f32 v76, v94, v95
	v_cvt_pk_bf16_f32 v77, v96, v97
	v_cvt_pk_bf16_f32 v70, v66, v67
	v_cvt_pk_bf16_f32 v71, v68, v69
	v_cvt_pk_bf16_f32 v72, v160, v161
	v_cvt_pk_bf16_f32 v73, v162, v73
	v_cvt_pk_bf16_f32 v66, v163, v164
	v_cvt_pk_bf16_f32 v67, v165, v166
	v_cvt_pk_bf16_f32 v68, v167, v168
	v_cvt_pk_bf16_f32 v69, v169, v158
	s_nop 1
	v_permlane32_swap_b32_e32 v82, v83
	s_cmp_eq_u32 s32, 0
	s_cbranch_scc1 .LBB0_815
	s_and_saveexec_b64 s[52:53], s[4:5]
	ds_write_b32 v149, v157 offset:128
	s_or_b64 exec, exec, s[52:53]
	s_waitcnt lgkmcnt(0)
	v_add_u32_e32 v96, v144, v0
	ds_read_b128 v[84:87], v96 offset:224
	ds_read_b128 v[88:91], v96 offset:192
	ds_read_b128 v[92:95], v96 offset:160
	ds_read_b128 v[158:161], v96 offset:128
	s_waitcnt lgkmcnt(0)
	v_pk_mul_f32 v[14:15], v[14:15], v[84:85]
	v_pk_mul_f32 v[10:11], v[10:11], v[88:89]
	v_pk_mul_f32 v[6:7], v[6:7], v[92:93]
	v_pk_mul_f32 v[16:17], v[16:17], v[86:87]
	v_pk_mul_f32 v[12:13], v[12:13], v[90:91]
	v_pk_mul_f32 v[8:9], v[8:9], v[94:95]
	v_pk_mul_f32 v[4:5], v[4:5], v[160:161]
	v_pk_mul_f32 v[2:3], v[2:3], v[158:159]
	v_pk_mul_f32 v[62:63], v[62:63], v[84:85]
	v_pk_mul_f32 v[58:59], v[58:59], v[88:89]
	v_pk_mul_f32 v[54:55], v[54:55], v[92:93]
	v_pk_mul_f32 v[64:65], v[64:65], v[86:87]
	v_pk_mul_f32 v[60:61], v[60:61], v[90:91]
	v_pk_mul_f32 v[56:57], v[56:57], v[94:95]
	v_pk_mul_f32 v[52:53], v[52:53], v[160:161]
	v_pk_mul_f32 v[50:51], v[50:51], v[158:159]
	v_pk_mul_f32 v[46:47], v[46:47], v[84:85]
	v_pk_mul_f32 v[42:43], v[42:43], v[88:89]
	v_pk_mul_f32 v[38:39], v[38:39], v[92:93]
	v_pk_mul_f32 v[48:49], v[48:49], v[86:87]
	v_pk_mul_f32 v[44:45], v[44:45], v[90:91]
	v_pk_mul_f32 v[40:41], v[40:41], v[94:95]
	v_pk_mul_f32 v[36:37], v[36:37], v[160:161]
	v_pk_mul_f32 v[34:35], v[34:35], v[158:159]
	v_pk_mul_f32 v[30:31], v[30:31], v[84:85]
	v_pk_mul_f32 v[26:27], v[26:27], v[88:89]
	v_pk_mul_f32 v[22:23], v[22:23], v[92:93]
	v_pk_mul_f32 v[32:33], v[32:33], v[86:87]
	v_pk_mul_f32 v[28:29], v[28:29], v[90:91]
	v_pk_mul_f32 v[24:25], v[24:25], v[94:95]
	v_pk_mul_f32 v[20:21], v[20:21], v[160:161]
	v_pk_mul_f32 v[18:19], v[18:19], v[158:159]
	v_mul_f32_e32 v156, v156, v157
; #define SBAR() __builtin_amdgcn_sched_barrier(0)
; template <int N> DI void wait_lgkm() { asm volatile("s_waitcnt lgkmcnt(%0)" :: "i"(N) : "memory"); }
; #define RESC(al) do { if (__any((al) < 1.f)) { if (hi == 0) al_l[r32] = (al); asm volatile("s_waitcnt lgkmcnt(0)" ::: "memory"); \
;     _Pragma("unroll") for (int d = 0; d < 4; ++d) _Pragma("unroll") for (int r = 0; r < 16; ++r) o[d][r] *= al_l[crow(r, hi)]; } } while (0)
; DI void pv_mm(f32x16* o, const s16x4* f, bf16x8 pa) {
;     ...
;     o[0] = __builtin_amdgcn_mfma_f32_32x32x16_bf16(pa, PK(f[0], f[1]), o[0], 0, 0, 0);
;     o[1] = __builtin_amdgcn_mfma_f32_32x32x16_bf16(pa, PK(f[2], f[3]), o[1], 0, 0, 0);
;     o[2] = __builtin_amdgcn_mfma_f32_32x32x16_bf16(pa, PK(f[4], f[5]), o[2], 0, 0, 0);
;     o[3] = __builtin_amdgcn_mfma_f32_32x32x16_bf16(pa, PK(f[6], f[7]), o[3], 0, 0, 0);
;     ...
; }
; DI void pv_d0(f32x16* o, int vb, bf16x8 pa0, bf16x8 pa1, bf16x8 pa2, bf16x8 pa3) {
;     s16x4 fa[8], fb[8];
;     v_rd8<0>(fa, vb);
;     v_rd8<1>(fb, vb); wait_lgkm<8>(); SBAR(); pv_mm(o, fa, pa0);
;     v_rd8<2>(fa, vb); wait_lgkm<8>(); SBAR(); pv_mm(o, fb, pa1);
;     v_rd8<3>(fb, vb); wait_lgkm<8>(); SBAR(); pv_mm(o, fa, pa2);
;     wait_lgkm<0>(); SBAR(); pv_mm(o, fb, pa3);
; }
; template <int DQK, int MODE>
; DI void attn_body(const AttnArgs& a, char* lds) {
;     ...
;         RESC(alpha);
;         pv_d0(o, vb0 + cur * SHM_V, pa0, pa1, pa2, pa3);
;         asm volatile("s_waitcnt vmcnt(0)" ::: "memory");
;         __syncthreads();
.LBB0_815:
	v_add_f32_e32 v82, v82, v83
	v_add_u32_e32 v83, s49, v154
	ds_read_b64_tr_b16 v[84:85], v83 offset:0
	ds_read_b64_tr_b16 v[86:87], v83 offset:0x800
	ds_read_b64_tr_b16 v[88:89], v83 offset:0x200
	ds_read_b64_tr_b16 v[90:91], v83 offset:0xa00
	ds_read_b64_tr_b16 v[92:93], v83 offset:0x400
	ds_read_b64_tr_b16 v[94:95], v83 offset:0xc00
	v_add_f32_e32 v82, v82, v156
	ds_read_b64_tr_b16 v[156:157], v83 offset:0x600
	ds_read_b64_tr_b16 v[158:159], v83 offset:0xe00
	ds_read_b64_tr_b16 v[160:161], v83 offset:0x1000
	ds_read_b64_tr_b16 v[162:163], v83 offset:0x1800
	ds_read_b64_tr_b16 v[164:165], v83 offset:0x1200
	ds_read_b64_tr_b16 v[166:167], v83 offset:0x1a00
	ds_read_b64_tr_b16 v[168:169], v83 offset:0x1400
	ds_read_b64_tr_b16 v[170:171], v83 offset:0x1c00
	ds_read_b64_tr_b16 v[172:173], v83 offset:0x1600
	ds_read_b64_tr_b16 v[174:175], v83 offset:0x1e00
	s_waitcnt lgkmcnt(8)
	v_mfma_f32_32x32x16_bf16 v[2:17], v[78:81], v[84:87], v[2:17]
	v_mfma_f32_32x32x16_bf16 v[50:65], v[78:81], v[88:91], v[50:65]
	v_mfma_f32_32x32x16_bf16 v[34:49], v[78:81], v[92:95], v[34:49]
	v_mfma_f32_32x32x16_bf16 v[18:33], v[78:81], v[156:159], v[18:33]
	ds_read_b64_tr_b16 v[78:79], v83 offset:0x2000
	ds_read_b64_tr_b16 v[80:81], v83 offset:0x2800
	ds_read_b64_tr_b16 v[84:85], v83 offset:0x2200
	ds_read_b64_tr_b16 v[86:87], v83 offset:0x2a00
	ds_read_b64_tr_b16 v[88:89], v83 offset:0x2400
	ds_read_b64_tr_b16 v[90:91], v83 offset:0x2c00
	ds_read_b64_tr_b16 v[92:93], v83 offset:0x2600
	ds_read_b64_tr_b16 v[94:95], v83 offset:0x2e00
	s_waitcnt lgkmcnt(8)
	v_mfma_f32_32x32x16_bf16 v[2:17], v[74:77], v[160:163], v[2:17]
	v_mfma_f32_32x32x16_bf16 v[50:65], v[74:77], v[164:167], v[50:65]
	v_mfma_f32_32x32x16_bf16 v[34:49], v[74:77], v[168:171], v[34:49]
	v_mfma_f32_32x32x16_bf16 v[18:33], v[74:77], v[172:175], v[18:33]
	ds_read_b64_tr_b16 v[74:75], v83 offset:0x3000
	ds_read_b64_tr_b16 v[76:77], v83 offset:0x3800
	ds_read_b64_tr_b16 v[156:157], v83 offset:0x3200
	ds_read_b64_tr_b16 v[158:159], v83 offset:0x3a00
	ds_read_b64_tr_b16 v[160:161], v83 offset:0x3400
	ds_read_b64_tr_b16 v[162:163], v83 offset:0x3c00
	ds_read_b64_tr_b16 v[164:165], v83 offset:0x3600
	ds_read_b64_tr_b16 v[166:167], v83 offset:0x3e00
	s_waitcnt lgkmcnt(8)
	v_mfma_f32_32x32x16_bf16 v[2:17], v[70:73], v[78:81], v[2:17]
	s_waitcnt lgkmcnt(0)
	v_mfma_f32_32x32x16_bf16 v[50:65], v[70:73], v[84:87], v[50:65]
	v_mfma_f32_32x32x16_bf16 v[34:49], v[70:73], v[88:91], v[34:49]
	v_mfma_f32_32x32x16_bf16 v[18:33], v[70:73], v[92:95], v[18:33]
	v_mfma_f32_32x32x16_bf16 v[2:17], v[66:69], v[74:77], v[2:17]
	s_waitcnt vmcnt(0)
	s_add_i32 s37, s37, 64
	s_add_u32 s89, s89, 0x170000
	s_addc_u32 s90, s90, 0
	s_cmp_eq_u32 s47, s36
	s_waitcnt vmcnt(0) lgkmcnt(0)
	s_barrier
	v_mfma_f32_32x32x16_bf16 v[50:65], v[66:69], v[156:159], v[50:65]
	v_mfma_f32_32x32x16_bf16 v[34:49], v[66:69], v[160:163], v[34:49]
	v_mfma_f32_32x32x16_bf16 v[18:33], v[66:69], v[164:167], v[18:33]
	s_cbranch_scc1 .LBB0_817
	v_mov_b32_e32 v156, v82
	s_branch .LBB0_807
